# peeled first K-tile per GEMM unit: first-touch MFMAs use C=0 (no per-unit accumulator zeroing), relaxed first-tile vmcnt; plus G1e tile rotation
# speedup vs baseline: 1.0039x; 1.0012x over previous
;     __device__ __forceinline__ void prefetch(Pre& p, const Unit& u, int wr, int fr, int fq) const { prefetch_ss(p, ss, u, wr, fr, fq); }
;     __device__ __forceinline__ void prefetch(Pre& p, const Unit& u, int wr, int fr, int fq) const { prefetch_ss(p, ss, u, wr, fr, fq); }
;     __device__ __forceinline__ void prefetch(Pre& p, const Unit& u, int wr, int fr, int fq) const { prefetch_ss(p, ss, u, wr, fr, fq); }
; #define PG8_STAGE(bufoff, gbase, voff) do { _Pragma("unroll") for (int _i = 0; _i < 2; ++_i) \
;         __builtin_amdgcn_global_load_lds((const unsigned*)((const char*)(gbase) + (voff)[_i]), (PG8_LAS unsigned*)(lds + (bufoff) + ldsw + _i * 8192), 16, 0, 0); } while (0)
; #define PG8_LDA(dst, b, h) do { _Pragma("unroll") for (int m = 0; m < 4; ++m) _Pragma("unroll") for (int k = 0; k < 2; ++k) dst[m][k] = *(const PG8_LAS bf16x8*)(lds + PG8_SA(b, h) + aoff + m * 2048 + k * 1024); } while (0)
; #define PG8_BAR __builtin_amdgcn_s_barrier()
; template <class Epi, class Sched, bool ALIGN_EPI = false, bool SP2 = false>
; __device__ __forceinline__ void gemm_phase(PG8_LAS unsigned char* lds, const Gemm g, const Sched& S, const Epi& E) {
;     ...
;         const bool has_next = S.next(ui + 1, nxt);
;         typename Epi::Pre pre; E.prefetch(pre, cur, wr, fr, fq);
;         const char* nA = has_next ? (const char*)g.A + (size_t)nxt.pm * tstep : cA; const char* nB = has_next ? (const char*)g.Bt + (size_t)nxt.pn * tstep : cB;
;         for (int t = 0; t < nt; t += 2) {
;             const bool last = (t == nt - 2);
;             const char* a1 = cA + (size_t)(t + 1) * kstep;
;             const char* a2 = last ? nA : cA + (size_t)(t + 2) * kstep; const char* b2 = last ? nB : cB + (size_t)(t + 2) * kstep;
;             const char* a3 = a2 + kstep; const char* b3 = b2 + kstep;
;             if (last && has_next) S.a_ready(nxt);
;             if constexpr (SP2) {
;             PG8_LDB(B0, 0, 0); PG8_LDB(B1, 0, 1); PG8_SCHED; PG8_LDA(At, 0, 0); PG8_STAGE(PG8_SA(1, 1), a1 + hstep, voffA);
;             PG8_WAIT_V(8); PG8_WAIT_L(0); PG8_BAR; PG8_MMA(0, 0, At, B0); PG8_MMA(0, 1, At, B1); PG8_BAR; PG8_SCHED;
;             PG8_LDA(At, 0, 1); PG8_STAGE(PG8_SB(0, 0), b2, voffB); PG8_STAGE(PG8_SB(0, 1), b2 + hstep, voffB); PG8_STAGE(PG8_SA(0, 0), a2, voffA);
;             PG8_WAIT_V(8); PG8_WAIT_L(0); PG8_BAR; PG8_MMA(1, 0, At, B0); PG8_MMA(1, 1, At, B1); PG8_BAR; PG8_SCHED;
.LBB0_53:
	v_lshl_add_u32 v142, s8, 8, v155
	v_ashrrev_i32_e32 v143, 31, v142
	v_lshl_add_u64 v[0:1], v[142:143], 3, v[136:137]
	global_load_dwordx2 v[152:153], v[0:1], off
	global_load_dwordx2 v[146:147], v[0:1], off offset:128
	s_ashr_i32 s59, s58, 31
	s_lshl_b64 s[20:21], s[58:59], 19
	s_add_u32 s60, s28, s20
	s_addc_u32 s61, s29, s21
	s_and_b64 s[20:21], s[42:43], exec
	s_cselect_b32 s26, s61, s65
	s_cselect_b32 s27, s60, s64
	s_ashr_i32 s57, s56, 31
	s_lshl_b64 s[20:21], s[56:57], 19
	s_add_u32 s62, s2, s20
	s_addc_u32 s63, s35, s21
	s_and_b64 s[20:21], s[42:43], exec
	s_cselect_b32 s36, s63, s45
	s_cselect_b32 s39, s62, s44
	s_add_u32 s57, s44, 0x100
	s_addc_u32 s59, s45, 0
	s_add_u32 s44, s64, 0x40080
	s_addc_u32 s45, s65, 0
	s_mov_b32 s76, -2
	s_cmp_eq_u32 s75, 1
	s_cbranch_scc1 .Lzero_g1o
.Lpeel_g1o:
	s_add_u32 s5, s44, 0xfffc0080
	s_addc_u32 s8, s45, -1
	s_add_i32 s10, 0, 0x10000
	s_cmp_eq_u32 s76, 12
	s_cselect_b32 s67, s26, s8
	s_cselect_b32 s66, s27, s5
	v_add_u32_e32 v154, s10, v157
	s_cselect_b32 s65, s36, s59
	s_cselect_b32 s64, s39, s57
	s_add_i32 s5, 0, 0x14000
	ds_read_b128 v[162:165], v154
	ds_read_b128 v[166:169], v154 offset:1024
	ds_read_b128 v[170:173], v154 offset:2048
	ds_read_b128 v[174:177], v154 offset:3072
	v_add_u32_e32 v154, s5, v157
	ds_read_b128 v[178:181], v154
	ds_read_b128 v[182:185], v154 offset:1024
	ds_read_b128 v[186:189], v154 offset:2048
	ds_read_b128 v[190:193], v154 offset:3072
	v_lshl_add_u64 v[194:195], s[44:45], 0, v[140:141]
	s_add_i32 m0, s69, 0xc000
	ds_read_b128 v[200:203], v161
	ds_read_b128 v[204:207], v161 offset:1024
	ds_read_b128 v[208:211], v161 offset:2048
	ds_read_b128 v[212:215], v161 offset:3072
	ds_read_b128 v[216:219], v161 offset:4096
	ds_read_b128 v[220:223], v161 offset:5120
	ds_read_b128 v[224:227], v161 offset:6144
	ds_read_b128 v[228:231], v161 offset:7168
	global_load_lds_dwordx4 v[194:195], off
	v_lshl_add_u64 v[194:195], s[44:45], 0, v[138:139]
	s_add_i32 m0, s69, 0xe000
	s_nop 0
	global_load_lds_dwordx4 v[194:195], off
	s_waitcnt vmcnt(26)
	s_waitcnt lgkmcnt(0)
	s_barrier
	s_setprio 1
	s_waitcnt lgkmcnt(0)
	v_mfma_f32_16x16x32_bf16 v[124:127], v[162:165], v[200:203], 0
	v_mfma_f32_16x16x32_bf16 v[120:123], v[170:173], v[200:203], 0
	v_mfma_f32_16x16x32_bf16 v[108:111], v[162:165], v[208:211], 0
	v_mfma_f32_16x16x32_bf16 v[104:107], v[170:173], v[208:211], 0
	v_mfma_f32_16x16x32_bf16 v[92:95], v[162:165], v[216:219], 0
	v_mfma_f32_16x16x32_bf16 v[88:91], v[170:173], v[216:219], 0
	v_mfma_f32_16x16x32_bf16 v[76:79], v[162:165], v[224:227], 0
	v_mfma_f32_16x16x32_bf16 v[72:75], v[170:173], v[224:227], 0
	v_mfma_f32_16x16x32_bf16 v[124:127], v[166:169], v[204:207], v[124:127]
	v_mfma_f32_16x16x32_bf16 v[120:123], v[174:177], v[204:207], v[120:123]
	v_mfma_f32_16x16x32_bf16 v[108:111], v[166:169], v[212:215], v[108:111]
	v_mfma_f32_16x16x32_bf16 v[104:107], v[174:177], v[212:215], v[104:107]
	v_mfma_f32_16x16x32_bf16 v[92:95], v[166:169], v[220:223], v[92:95]
	v_mfma_f32_16x16x32_bf16 v[88:91], v[174:177], v[220:223], v[88:91]
	v_mfma_f32_16x16x32_bf16 v[76:79], v[166:169], v[228:231], v[76:79]
	v_mfma_f32_16x16x32_bf16 v[72:75], v[174:177], v[228:231], v[72:75]
	s_setprio 0
	s_setprio 1
	v_mfma_f32_16x16x32_bf16 v[116:119], v[178:181], v[200:203], 0
	v_mfma_f32_16x16x32_bf16 v[112:115], v[186:189], v[200:203], 0
	v_mfma_f32_16x16x32_bf16 v[100:103], v[178:181], v[208:211], 0
	v_mfma_f32_16x16x32_bf16 v[96:99], v[186:189], v[208:211], 0
	v_mfma_f32_16x16x32_bf16 v[84:87], v[178:181], v[216:219], 0
	v_mfma_f32_16x16x32_bf16 v[80:83], v[186:189], v[216:219], 0
	v_mfma_f32_16x16x32_bf16 v[68:71], v[178:181], v[224:227], 0
	v_mfma_f32_16x16x32_bf16 v[64:67], v[186:189], v[224:227], 0
	v_mfma_f32_16x16x32_bf16 v[116:119], v[182:185], v[204:207], v[116:119]
	v_mfma_f32_16x16x32_bf16 v[112:115], v[190:193], v[204:207], v[112:115]
	v_mfma_f32_16x16x32_bf16 v[100:103], v[182:185], v[212:215], v[100:103]
	v_mfma_f32_16x16x32_bf16 v[96:99], v[190:193], v[212:215], v[96:99]
	v_mfma_f32_16x16x32_bf16 v[84:87], v[182:185], v[220:223], v[84:87]
	v_mfma_f32_16x16x32_bf16 v[80:83], v[190:193], v[220:223], v[80:83]
	v_mfma_f32_16x16x32_bf16 v[68:71], v[182:185], v[228:231], v[68:71]
	v_mfma_f32_16x16x32_bf16 v[64:67], v[190:193], v[228:231], v[64:67]
	s_setprio 0
	s_barrier
	s_add_i32 s8, s10, s68
	v_lshl_add_u64 v[194:195], s[64:65], 0, v[132:133]
	s_mov_b32 m0, s8
	ds_read_b128 v[200:203], v161 offset:16384
	ds_read_b128 v[204:207], v161 offset:17408
	ds_read_b128 v[208:211], v161 offset:18432
	ds_read_b128 v[212:215], v161 offset:19456
	ds_read_b128 v[216:219], v161 offset:20480
	ds_read_b128 v[220:223], v161 offset:21504
	ds_read_b128 v[224:227], v161 offset:22528
	ds_read_b128 v[228:231], v161 offset:23552
	global_load_lds_dwordx4 v[194:195], off
	s_add_i32 m0, s8, 0x2000
	s_add_u32 s20, s64, 0x40000
	v_lshl_add_u64 v[240:241], s[64:65], 0, v[128:129]
	s_addc_u32 s21, s65, 0
	s_add_i32 s5, s5, s68
	global_load_lds_dwordx4 v[240:241], off
	v_lshl_add_u64 v[242:243], s[20:21], 0, v[132:133]
	s_mov_b32 m0, s5
	v_lshl_add_u64 v[244:245], s[66:67], 0, v[130:131]
	global_load_lds_dwordx4 v[242:243], off
	v_lshl_add_u64 v[242:243], s[20:21], 0, v[128:129]
	s_add_i32 m0, s5, 0x2000
	s_nop 0
	global_load_lds_dwordx4 v[242:243], off
	v_lshl_add_u64 v[242:243], s[66:67], 0, v[134:135]
	s_mov_b32 m0, s69
	s_nop 0
	global_load_lds_dwordx4 v[242:243], off
	s_mov_b32 m0, s70
	s_nop 0
	global_load_lds_dwordx4 v[244:245], off
	s_waitcnt vmcnt(26)
	s_waitcnt lgkmcnt(0)
	s_barrier
; #define PG8_STAGE(bufoff, gbase, voff) do { _Pragma("unroll") for (int _i = 0; _i < 2; ++_i) \
;         __builtin_amdgcn_global_load_lds((const unsigned*)((const char*)(gbase) + (voff)[_i]), (PG8_LAS unsigned*)(lds + (bufoff) + ldsw + _i * 8192), 16, 0, 0); } while (0)
; #define PG8_LDA(dst, b, h) do { _Pragma("unroll") for (int m = 0; m < 4; ++m) _Pragma("unroll") for (int k = 0; k < 2; ++k) dst[m][k] = *(const PG8_LAS bf16x8*)(lds + PG8_SA(b, h) + aoff + m * 2048 + k * 1024); } while (0)
; #define PG8_MMA(ai, bj, At, Bt) do { __builtin_amdgcn_s_setprio(1); _Pragma("unroll") for (int m = 0; m < 4; ++m) _Pragma("unroll") for (int n = 0; n < 2; ++n) _Pragma("unroll") for (int k = 0; k < 2; ++k) \
;         acc[ai][bj][m][n] = __builtin_amdgcn_mfma_f32_16x16x32_bf16(Bt[n][k], At[m][k], acc[ai][bj][m][n], 0, 0, 0); __builtin_amdgcn_s_setprio(0); } while (0)
; #define PG8_WAIT_V(n) asm volatile("s_waitcnt vmcnt(" #n ")" ::: "memory")
; #define PG8_WAIT_L(n) asm volatile("s_waitcnt lgkmcnt(" #n ")" ::: "memory")
; #define PG8_BAR __builtin_amdgcn_s_barrier()
; #define PG8_SCHED __builtin_amdgcn_sched_barrier(0)
; template <class Epi, class Sched, bool ALIGN_EPI = false, bool SP2 = false>
; __device__ __forceinline__ void gemm_phase(PG8_LAS unsigned char* lds, const Gemm g, const Sched& S, const Epi& E) {
;     ...
;             PG8_WAIT_V(8); PG8_WAIT_L(0); PG8_BAR; PG8_MMA(0, 0, At, B0); PG8_MMA(0, 1, At, B1); PG8_BAR; PG8_SCHED;
;             PG8_LDA(At, 0, 1); PG8_STAGE(PG8_SB(0, 0), b2, voffB); PG8_STAGE(PG8_SB(0, 1), b2 + hstep, voffB); PG8_STAGE(PG8_SA(0, 0), a2, voffA);
;             PG8_WAIT_V(8); PG8_WAIT_L(0); PG8_BAR; PG8_MMA(1, 0, At, B0); PG8_MMA(1, 1, At, B1); PG8_BAR; PG8_SCHED;
;     ...
; #pragma unroll
;         for (int a = 0; a < 2; ++a)
; #pragma unroll
;             for (int b = 0; b < 2; ++b)
; #pragma unroll
;                 for (int m = 0; m < 4; ++m)
; #pragma unroll
;                     for (int n = 0; n < 2; ++n) acc[a][b][m][n] = (f32x4){0.f, 0.f, 0.f, 0.f};
	s_setprio 1
	s_waitcnt lgkmcnt(0)
	v_mfma_f32_16x16x32_bf16 v[60:63], v[162:165], v[200:203], 0
	v_mfma_f32_16x16x32_bf16 v[56:59], v[170:173], v[200:203], 0
	v_mfma_f32_16x16x32_bf16 v[44:47], v[162:165], v[208:211], 0
	v_mfma_f32_16x16x32_bf16 v[40:43], v[170:173], v[208:211], 0
	v_mfma_f32_16x16x32_bf16 v[28:31], v[162:165], v[216:219], 0
	v_mfma_f32_16x16x32_bf16 v[24:27], v[170:173], v[216:219], 0
	v_mfma_f32_16x16x32_bf16 v[12:15], v[162:165], v[224:227], 0
	v_mfma_f32_16x16x32_bf16 v[8:11], v[170:173], v[224:227], 0
	v_mfma_f32_16x16x32_bf16 v[60:63], v[166:169], v[204:207], v[60:63]
	v_mfma_f32_16x16x32_bf16 v[56:59], v[174:177], v[204:207], v[56:59]
	v_mfma_f32_16x16x32_bf16 v[44:47], v[166:169], v[212:215], v[44:47]
	v_mfma_f32_16x16x32_bf16 v[40:43], v[174:177], v[212:215], v[40:43]
	v_mfma_f32_16x16x32_bf16 v[28:31], v[166:169], v[220:223], v[28:31]
	v_mfma_f32_16x16x32_bf16 v[24:27], v[174:177], v[220:223], v[24:27]
	v_mfma_f32_16x16x32_bf16 v[12:15], v[166:169], v[228:231], v[12:15]
	v_mfma_f32_16x16x32_bf16 v[8:11], v[174:177], v[228:231], v[8:11]
	s_setprio 0
	s_setprio 1
	v_mfma_f32_16x16x32_bf16 v[52:55], v[178:181], v[200:203], 0
	v_mfma_f32_16x16x32_bf16 v[48:51], v[186:189], v[200:203], 0
	v_mfma_f32_16x16x32_bf16 v[36:39], v[178:181], v[208:211], 0
	v_mfma_f32_16x16x32_bf16 v[32:35], v[186:189], v[208:211], 0
	v_mfma_f32_16x16x32_bf16 v[20:23], v[178:181], v[216:219], 0
	v_mfma_f32_16x16x32_bf16 v[16:19], v[186:189], v[216:219], 0
	v_mfma_f32_16x16x32_bf16 v[4:7], v[178:181], v[224:227], 0
	v_mfma_f32_16x16x32_bf16 v[0:3], v[186:189], v[224:227], 0
	v_mfma_f32_16x16x32_bf16 v[52:55], v[182:185], v[204:207], v[52:55]
	v_mfma_f32_16x16x32_bf16 v[48:51], v[190:193], v[204:207], v[48:51]
	v_mfma_f32_16x16x32_bf16 v[36:39], v[182:185], v[212:215], v[36:39]
	v_mfma_f32_16x16x32_bf16 v[32:35], v[190:193], v[212:215], v[32:35]
	v_mfma_f32_16x16x32_bf16 v[20:23], v[182:185], v[220:223], v[20:23]
	v_mfma_f32_16x16x32_bf16 v[16:19], v[190:193], v[220:223], v[16:19]
	v_mfma_f32_16x16x32_bf16 v[4:7], v[182:185], v[228:231], v[4:7]
	v_mfma_f32_16x16x32_bf16 v[0:3], v[190:193], v[228:231], v[0:3]
	s_setprio 0
	s_barrier
	s_branch .Lmid_g1o
.Lzero_g1o:
	v_mov_b32_e32 v0, 0
	v_mov_b32_e32 v1, v0
	v_mov_b32_e32 v2, v0
	v_mov_b32_e32 v3, v0
	v_mov_b32_e32 v4, v0
	v_mov_b32_e32 v5, v0
	v_mov_b32_e32 v6, v0
	v_mov_b32_e32 v7, v0
	v_mov_b32_e32 v16, v0
	v_mov_b32_e32 v17, v0
	v_mov_b32_e32 v18, v0
	v_mov_b32_e32 v19, v0
	v_mov_b32_e32 v20, v0
	v_mov_b32_e32 v21, v0
	v_mov_b32_e32 v22, v0
	v_mov_b32_e32 v23, v0
	v_mov_b32_e32 v32, v0
	v_mov_b32_e32 v33, v0
	v_mov_b32_e32 v34, v0
	v_mov_b32_e32 v35, v0
	v_mov_b32_e32 v36, v0
	v_mov_b32_e32 v37, v0
	v_mov_b32_e32 v38, v0
	v_mov_b32_e32 v39, v0
	v_mov_b32_e32 v48, v0
	v_mov_b32_e32 v49, v0
	v_mov_b32_e32 v50, v0
	v_mov_b32_e32 v51, v0
	v_mov_b32_e32 v52, v0
	v_mov_b32_e32 v53, v0
	v_mov_b32_e32 v54, v0
	v_mov_b32_e32 v55, v0
	v_mov_b32_e32 v8, v0
	v_mov_b32_e32 v9, v0
	v_mov_b32_e32 v10, v0
	v_mov_b32_e32 v11, v0
	v_mov_b32_e32 v12, v0
	v_mov_b32_e32 v13, v0
	v_mov_b32_e32 v14, v0
	v_mov_b32_e32 v15, v0
	v_mov_b32_e32 v24, v0
	v_mov_b32_e32 v25, v0
	v_mov_b32_e32 v26, v0
	v_mov_b32_e32 v27, v0
	v_mov_b32_e32 v28, v0
	v_mov_b32_e32 v29, v0
	v_mov_b32_e32 v30, v0
	v_mov_b32_e32 v31, v0
	v_mov_b32_e32 v40, v0
	v_mov_b32_e32 v41, v0
	v_mov_b32_e32 v42, v0
	v_mov_b32_e32 v43, v0
	v_mov_b32_e32 v44, v0
	v_mov_b32_e32 v45, v0
	v_mov_b32_e32 v46, v0
	v_mov_b32_e32 v47, v0
	v_mov_b32_e32 v56, v0
	v_mov_b32_e32 v57, v0
	v_mov_b32_e32 v58, v0
	v_mov_b32_e32 v59, v0
	v_mov_b32_e32 v60, v0
	v_mov_b32_e32 v61, v0
	v_mov_b32_e32 v62, v0
	v_mov_b32_e32 v63, v0
	v_mov_b32_e32 v64, v0
	v_mov_b32_e32 v65, v0
	v_mov_b32_e32 v66, v0
	v_mov_b32_e32 v67, v0
	v_mov_b32_e32 v68, v0
	v_mov_b32_e32 v69, v0
	v_mov_b32_e32 v70, v0
	v_mov_b32_e32 v71, v0
	v_mov_b32_e32 v80, v0
	v_mov_b32_e32 v81, v0
	v_mov_b32_e32 v82, v0
	v_mov_b32_e32 v83, v0
	v_mov_b32_e32 v84, v0
	v_mov_b32_e32 v85, v0
	v_mov_b32_e32 v86, v0
	v_mov_b32_e32 v87, v0
	v_mov_b32_e32 v96, v0
	v_mov_b32_e32 v97, v0
	v_mov_b32_e32 v98, v0
	v_mov_b32_e32 v99, v0
	v_mov_b32_e32 v100, v0
	v_mov_b32_e32 v101, v0
	v_mov_b32_e32 v102, v0
	v_mov_b32_e32 v103, v0
	v_mov_b32_e32 v112, v0
	v_mov_b32_e32 v113, v0
	v_mov_b32_e32 v114, v0
	v_mov_b32_e32 v115, v0
	v_mov_b32_e32 v116, v0
	v_mov_b32_e32 v117, v0
	v_mov_b32_e32 v118, v0
	v_mov_b32_e32 v119, v0
	v_mov_b32_e32 v72, v0
	v_mov_b32_e32 v73, v0
	v_mov_b32_e32 v74, v0
	v_mov_b32_e32 v75, v0
	v_mov_b32_e32 v76, v0
	v_mov_b32_e32 v77, v0
	v_mov_b32_e32 v78, v0
	v_mov_b32_e32 v79, v0
	v_mov_b32_e32 v88, v0
	v_mov_b32_e32 v89, v0
	v_mov_b32_e32 v90, v0
	v_mov_b32_e32 v91, v0
	v_mov_b32_e32 v92, v0
	v_mov_b32_e32 v93, v0
	v_mov_b32_e32 v94, v0
	v_mov_b32_e32 v95, v0
	v_mov_b32_e32 v104, v0
	v_mov_b32_e32 v105, v0
	v_mov_b32_e32 v106, v0
	v_mov_b32_e32 v107, v0
	v_mov_b32_e32 v108, v0
	v_mov_b32_e32 v109, v0
	v_mov_b32_e32 v110, v0
	v_mov_b32_e32 v111, v0
	v_mov_b32_e32 v120, v0
	v_mov_b32_e32 v121, v0
	v_mov_b32_e32 v122, v0
	v_mov_b32_e32 v123, v0
	v_mov_b32_e32 v124, v0
	v_mov_b32_e32 v125, v0
	v_mov_b32_e32 v126, v0
	v_mov_b32_e32 v127, v0

; #define PG8_STAGE(bufoff, gbase, voff) do { _Pragma("unroll") for (int _i = 0; _i < 2; ++_i) \
;         __builtin_amdgcn_global_load_lds((const unsigned*)((const char*)(gbase) + (voff)[_i]), (PG8_LAS unsigned*)(lds + (bufoff) + ldsw + _i * 8192), 16, 0, 0); } while (0)
; #define PG8_LDA(dst, b, h) do { _Pragma("unroll") for (int m = 0; m < 4; ++m) _Pragma("unroll") for (int k = 0; k < 2; ++k) dst[m][k] = *(const PG8_LAS bf16x8*)(lds + PG8_SA(b, h) + aoff + m * 2048 + k * 1024); } while (0)
; #define PG8_LDB(dst, b, h) do { _Pragma("unroll") for (int n = 0; n < 2; ++n) _Pragma("unroll") for (int k = 0; k < 2; ++k) dst[n][k] = *(const PG8_LAS bf16x8*)(lds + PG8_SB(b, h) + boff + n * 2048 + k * 1024); } while (0)
; #define PG8_MMA(ai, bj, At, Bt) do { __builtin_amdgcn_s_setprio(1); _Pragma("unroll") for (int m = 0; m < 4; ++m) _Pragma("unroll") for (int n = 0; n < 2; ++n) _Pragma("unroll") for (int k = 0; k < 2; ++k) \
;         acc[ai][bj][m][n] = __builtin_amdgcn_mfma_f32_16x16x32_bf16(Bt[n][k], At[m][k], acc[ai][bj][m][n], 0, 0, 0); __builtin_amdgcn_s_setprio(0); } while (0)
; #define PG8_WAIT_V(n) asm volatile("s_waitcnt vmcnt(" #n ")" ::: "memory")
; #define PG8_WAIT_L(n) asm volatile("s_waitcnt lgkmcnt(" #n ")" ::: "memory")
; #define PG8_BAR __builtin_amdgcn_s_barrier()
; #define PG8_SCHED __builtin_amdgcn_sched_barrier(0)
; template <class Epi, class Sched, bool ALIGN_EPI = false, bool SP2 = false>
; __device__ __forceinline__ void gemm_phase(PG8_LAS unsigned char* lds, const Gemm g, const Sched& S, const Epi& E) {
;     ...
;             PG8_LDB(B0, 1, 0); PG8_LDB(B1, 1, 1); PG8_SCHED; PG8_LDA(At, 1, 0); PG8_STAGE(PG8_SA(0, 1), a2 + hstep, voffA);
;             PG8_WAIT_V(8); PG8_WAIT_L(0); PG8_BAR; PG8_MMA(0, 0, At, B0); PG8_MMA(0, 1, At, B1); PG8_BAR; PG8_SCHED;
.Lmid_g1o:
	s_add_i32 s5, 0, 0x18000
	v_add_u32_e32 v154, s5, v157
	s_add_i32 s8, 0, 0x1c000
	ds_read_b128 v[162:165], v154
	ds_read_b128 v[166:169], v154 offset:1024
	ds_read_b128 v[170:173], v154 offset:2048
	ds_read_b128 v[174:177], v154 offset:3072
	v_add_u32_e32 v154, s8, v157
	ds_read_b128 v[178:181], v154
	ds_read_b128 v[182:185], v154 offset:1024
	ds_read_b128 v[186:189], v154 offset:2048
	ds_read_b128 v[190:193], v154 offset:3072
	s_add_u32 s20, s66, 0x40000
	s_addc_u32 s21, s67, 0
	s_mov_b32 m0, s71
	v_lshl_add_u64 v[246:247], s[20:21], 0, v[134:135]
	ds_read_b128 v[200:203], v161 offset:32768
	ds_read_b128 v[204:207], v161 offset:33792
	ds_read_b128 v[208:211], v161 offset:34816
	ds_read_b128 v[212:215], v161 offset:35840
	ds_read_b128 v[216:219], v161 offset:36864
	ds_read_b128 v[220:223], v161 offset:37888
	ds_read_b128 v[224:227], v161 offset:38912
	ds_read_b128 v[228:231], v161 offset:39936
	global_load_lds_dwordx4 v[246:247], off
	v_lshl_add_u64 v[246:247], s[20:21], 0, v[130:131]
	s_mov_b32 m0, s72
	s_nop 0
	global_load_lds_dwordx4 v[246:247], off
	s_waitcnt vmcnt(8)
	s_waitcnt lgkmcnt(0)
	s_barrier
	s_setprio 1
	s_waitcnt lgkmcnt(0)
	v_mfma_f32_16x16x32_bf16 v[124:127], v[162:165], v[200:203], v[124:127]
	v_mfma_f32_16x16x32_bf16 v[120:123], v[170:173], v[200:203], v[120:123]
	v_mfma_f32_16x16x32_bf16 v[108:111], v[162:165], v[208:211], v[108:111]
	v_mfma_f32_16x16x32_bf16 v[104:107], v[170:173], v[208:211], v[104:107]
	v_mfma_f32_16x16x32_bf16 v[92:95], v[162:165], v[216:219], v[92:95]
	v_mfma_f32_16x16x32_bf16 v[88:91], v[170:173], v[216:219], v[88:91]
	v_mfma_f32_16x16x32_bf16 v[76:79], v[162:165], v[224:227], v[76:79]
	v_mfma_f32_16x16x32_bf16 v[72:75], v[170:173], v[224:227], v[72:75]
	v_mfma_f32_16x16x32_bf16 v[124:127], v[166:169], v[204:207], v[124:127]
	v_mfma_f32_16x16x32_bf16 v[120:123], v[174:177], v[204:207], v[120:123]
	v_mfma_f32_16x16x32_bf16 v[108:111], v[166:169], v[212:215], v[108:111]
	v_mfma_f32_16x16x32_bf16 v[104:107], v[174:177], v[212:215], v[104:107]
	v_mfma_f32_16x16x32_bf16 v[92:95], v[166:169], v[220:223], v[92:95]
	v_mfma_f32_16x16x32_bf16 v[88:91], v[174:177], v[220:223], v[88:91]
	v_mfma_f32_16x16x32_bf16 v[76:79], v[166:169], v[228:231], v[76:79]
	v_mfma_f32_16x16x32_bf16 v[72:75], v[174:177], v[228:231], v[72:75]
	s_setprio 0
	s_setprio 1
	v_mfma_f32_16x16x32_bf16 v[116:119], v[178:181], v[200:203], v[116:119]
	v_mfma_f32_16x16x32_bf16 v[112:115], v[186:189], v[200:203], v[112:115]
	v_mfma_f32_16x16x32_bf16 v[100:103], v[178:181], v[208:211], v[100:103]
	v_mfma_f32_16x16x32_bf16 v[96:99], v[186:189], v[208:211], v[96:99]
	v_mfma_f32_16x16x32_bf16 v[84:87], v[178:181], v[216:219], v[84:87]
	v_mfma_f32_16x16x32_bf16 v[80:83], v[186:189], v[216:219], v[80:83]
	v_mfma_f32_16x16x32_bf16 v[68:71], v[178:181], v[224:227], v[68:71]
	v_mfma_f32_16x16x32_bf16 v[64:67], v[186:189], v[224:227], v[64:67]
	v_mfma_f32_16x16x32_bf16 v[116:119], v[182:185], v[204:207], v[116:119]
	v_mfma_f32_16x16x32_bf16 v[112:115], v[190:193], v[204:207], v[112:115]
	v_mfma_f32_16x16x32_bf16 v[100:103], v[182:185], v[212:215], v[100:103]
	v_mfma_f32_16x16x32_bf16 v[96:99], v[190:193], v[212:215], v[96:99]
	v_mfma_f32_16x16x32_bf16 v[84:87], v[182:185], v[220:223], v[84:87]
	v_mfma_f32_16x16x32_bf16 v[80:83], v[190:193], v[220:223], v[80:83]
	v_mfma_f32_16x16x32_bf16 v[68:71], v[182:185], v[228:231], v[68:71]
	v_mfma_f32_16x16x32_bf16 v[64:67], v[190:193], v[228:231], v[64:67]
	s_setprio 0
	s_barrier
; #define PG8_STAGE(bufoff, gbase, voff) do { _Pragma("unroll") for (int _i = 0; _i < 2; ++_i) \
;         __builtin_amdgcn_global_load_lds((const unsigned*)((const char*)(gbase) + (voff)[_i]), (PG8_LAS unsigned*)(lds + (bufoff) + ldsw + _i * 8192), 16, 0, 0); } while (0)
; #define PG8_LDA(dst, b, h) do { _Pragma("unroll") for (int m = 0; m < 4; ++m) _Pragma("unroll") for (int k = 0; k < 2; ++k) dst[m][k] = *(const PG8_LAS bf16x8*)(lds + PG8_SA(b, h) + aoff + m * 2048 + k * 1024); } while (0)
; #define PG8_MMA(ai, bj, At, Bt) do { __builtin_amdgcn_s_setprio(1); _Pragma("unroll") for (int m = 0; m < 4; ++m) _Pragma("unroll") for (int n = 0; n < 2; ++n) _Pragma("unroll") for (int k = 0; k < 2; ++k) \
;         acc[ai][bj][m][n] = __builtin_amdgcn_mfma_f32_16x16x32_bf16(Bt[n][k], At[m][k], acc[ai][bj][m][n], 0, 0, 0); __builtin_amdgcn_s_setprio(0); } while (0)
; #define PG8_WAIT_V(n) asm volatile("s_waitcnt vmcnt(" #n ")" ::: "memory")
; #define PG8_WAIT_L(n) asm volatile("s_waitcnt lgkmcnt(" #n ")" ::: "memory")
; #define PG8_BAR __builtin_amdgcn_s_barrier()
; #define PG8_SCHED __builtin_amdgcn_sched_barrier(0)
; template <class Epi, class Sched, bool ALIGN_EPI = false, bool SP2 = false>
; __device__ __forceinline__ void gemm_phase(PG8_LAS unsigned char* lds, const Gemm g, const Sched& S, const Epi& E) {
;     ...
;         for (int t = 0; t < nt; t += 2) {
;     ...
;             PG8_LDA(At, 1, 1); PG8_STAGE(PG8_SB(1, 0), b3, voffB); PG8_STAGE(PG8_SB(1, 1), b3 + hstep, voffB); PG8_STAGE(PG8_SA(1, 0), a3, voffA);
;             PG8_WAIT_V(8); PG8_WAIT_L(0); PG8_BAR; PG8_MMA(1, 0, At, B0); PG8_MMA(1, 1, At, B1); PG8_BAR; PG8_SCHED;
;     ...
;         if constexpr (ALIGN_EPI) { if (wr == 0) PG8_BAR; }
	s_add_i32 s5, s5, s68
	v_lshl_add_u64 v[194:195], v[194:195], 0, s[22:23]
	s_mov_b32 m0, s5
	ds_read_b128 v[200:203], v161 offset:49152
	ds_read_b128 v[204:207], v161 offset:50176
	ds_read_b128 v[208:211], v161 offset:51200
	ds_read_b128 v[212:215], v161 offset:52224
	ds_read_b128 v[216:219], v161 offset:53248
	ds_read_b128 v[220:223], v161 offset:54272
	ds_read_b128 v[224:227], v161 offset:55296
	ds_read_b128 v[228:231], v161 offset:56320
	global_load_lds_dwordx4 v[194:195], off
	s_add_i32 m0, s5, 0x2000
	s_add_u32 s20, s64, 0x40080
	v_lshl_add_u64 v[194:195], v[240:241], 0, s[22:23]
	s_addc_u32 s21, s65, 0
	s_add_i32 s5, s8, s68
	global_load_lds_dwordx4 v[194:195], off
	v_lshl_add_u64 v[194:195], s[20:21], 0, v[132:133]
	s_mov_b32 m0, s5
	s_nop 0
	global_load_lds_dwordx4 v[194:195], off
	v_lshl_add_u64 v[194:195], s[20:21], 0, v[128:129]
	s_add_i32 m0, s5, 0x2000
	s_nop 0
	global_load_lds_dwordx4 v[194:195], off
	v_lshl_add_u64 v[194:195], v[242:243], 0, s[22:23]
	s_mov_b32 m0, s73
	s_nop 0
	global_load_lds_dwordx4 v[194:195], off
	v_lshl_add_u64 v[194:195], v[244:245], 0, s[22:23]
	s_mov_b32 m0, s74
	s_nop 0
	global_load_lds_dwordx4 v[194:195], off
	s_waitcnt vmcnt(8)
	s_waitcnt lgkmcnt(0)
	s_barrier
	s_setprio 1
	s_waitcnt lgkmcnt(0)
	v_mfma_f32_16x16x32_bf16 v[60:63], v[162:165], v[200:203], v[60:63]
	v_mfma_f32_16x16x32_bf16 v[56:59], v[170:173], v[200:203], v[56:59]
	v_mfma_f32_16x16x32_bf16 v[44:47], v[162:165], v[208:211], v[44:47]
	v_mfma_f32_16x16x32_bf16 v[40:43], v[170:173], v[208:211], v[40:43]
	v_mfma_f32_16x16x32_bf16 v[28:31], v[162:165], v[216:219], v[28:31]
	v_mfma_f32_16x16x32_bf16 v[24:27], v[170:173], v[216:219], v[24:27]
	v_mfma_f32_16x16x32_bf16 v[12:15], v[162:165], v[224:227], v[12:15]
	v_mfma_f32_16x16x32_bf16 v[8:11], v[170:173], v[224:227], v[8:11]
	v_mfma_f32_16x16x32_bf16 v[60:63], v[166:169], v[204:207], v[60:63]
	v_mfma_f32_16x16x32_bf16 v[56:59], v[174:177], v[204:207], v[56:59]
	v_mfma_f32_16x16x32_bf16 v[44:47], v[166:169], v[212:215], v[44:47]
	v_mfma_f32_16x16x32_bf16 v[40:43], v[174:177], v[212:215], v[40:43]
	v_mfma_f32_16x16x32_bf16 v[28:31], v[166:169], v[220:223], v[28:31]
	v_mfma_f32_16x16x32_bf16 v[24:27], v[174:177], v[220:223], v[24:27]
	v_mfma_f32_16x16x32_bf16 v[12:15], v[166:169], v[228:231], v[12:15]
	v_mfma_f32_16x16x32_bf16 v[8:11], v[174:177], v[228:231], v[8:11]
	s_setprio 0
	s_setprio 1
	v_mfma_f32_16x16x32_bf16 v[52:55], v[178:181], v[200:203], v[52:55]
	v_mfma_f32_16x16x32_bf16 v[48:51], v[186:189], v[200:203], v[48:51]
	v_mfma_f32_16x16x32_bf16 v[36:39], v[178:181], v[208:211], v[36:39]
	v_mfma_f32_16x16x32_bf16 v[32:35], v[186:189], v[208:211], v[32:35]
	v_mfma_f32_16x16x32_bf16 v[20:23], v[178:181], v[216:219], v[20:23]
	v_mfma_f32_16x16x32_bf16 v[16:19], v[186:189], v[216:219], v[16:19]
	v_mfma_f32_16x16x32_bf16 v[4:7], v[178:181], v[224:227], v[4:7]
	v_mfma_f32_16x16x32_bf16 v[0:3], v[186:189], v[224:227], v[0:3]
	v_mfma_f32_16x16x32_bf16 v[52:55], v[182:185], v[204:207], v[52:55]
	v_mfma_f32_16x16x32_bf16 v[48:51], v[190:193], v[204:207], v[48:51]
	v_mfma_f32_16x16x32_bf16 v[36:39], v[182:185], v[212:215], v[36:39]
	v_mfma_f32_16x16x32_bf16 v[32:35], v[190:193], v[212:215], v[32:35]
	v_mfma_f32_16x16x32_bf16 v[20:23], v[182:185], v[220:223], v[20:23]
	v_mfma_f32_16x16x32_bf16 v[16:19], v[190:193], v[220:223], v[16:19]
	v_mfma_f32_16x16x32_bf16 v[4:7], v[182:185], v[228:231], v[4:7]
	v_mfma_f32_16x16x32_bf16 v[0:3], v[190:193], v[228:231], v[0:3]
	s_setprio 0
	s_barrier
	s_add_i32 s76, s76, 2
	s_add_u32 s57, s57, 0x100
	s_addc_u32 s59, s59, 0
	s_add_u32 s44, s44, 0x100
	s_addc_u32 s45, s45, 0
	s_cmp_gt_u32 s76, 13
	s_cbranch_scc0 .LBB0_54
	s_and_b64 vcc, exec, s[54:55]
	s_cbranch_vccz .LBB0_57
	s_barrier

;     __device__ __forceinline__ void prefetch(Pre& p, const Unit& u, int wr, int fr, int fq) const { prefetch_ss(p, ss, u, wr, fr, fq); }
;     __device__ __forceinline__ void prefetch(Pre& p, const Unit& u, int wr, int fr, int fq) const { prefetch_ss(p, ss, u, wr, fr, fq); }
;     __device__ __forceinline__ void prefetch(Pre& p, const Unit& u, int wr, int fr, int fq) const { prefetch_ss(p, ss, u, wr, fr, fq); }
; #define PG8_STAGE(bufoff, gbase, voff) do { _Pragma("unroll") for (int _i = 0; _i < 2; ++_i) \
;         __builtin_amdgcn_global_load_lds((const unsigned*)((const char*)(gbase) + (voff)[_i]), (PG8_LAS unsigned*)(lds + (bufoff) + ldsw + _i * 8192), 16, 0, 0); } while (0)
; #define PG8_LDA(dst, b, h) do { _Pragma("unroll") for (int m = 0; m < 4; ++m) _Pragma("unroll") for (int k = 0; k < 2; ++k) dst[m][k] = *(const PG8_LAS bf16x8*)(lds + PG8_SA(b, h) + aoff + m * 2048 + k * 1024); } while (0)
; #define PG8_BAR __builtin_amdgcn_s_barrier()
; template <class Epi, class Sched, bool ALIGN_EPI = false, bool SP2 = false>
; __device__ __forceinline__ void gemm_phase(PG8_LAS unsigned char* lds, const Gemm g, const Sched& S, const Epi& E) {
;     ...
;         const bool has_next = S.next(ui + 1, nxt);
;         typename Epi::Pre pre; E.prefetch(pre, cur, wr, fr, fq);
;         const char* nA = has_next ? (const char*)g.A + (size_t)nxt.pm * tstep : cA; const char* nB = has_next ? (const char*)g.Bt + (size_t)nxt.pn * tstep : cB;
;         for (int t = 0; t < nt; t += 2) {
;             const bool last = (t == nt - 2);
;             const char* a1 = cA + (size_t)(t + 1) * kstep;
;             const char* a2 = last ? nA : cA + (size_t)(t + 2) * kstep; const char* b2 = last ? nB : cB + (size_t)(t + 2) * kstep;
;             const char* a3 = a2 + kstep; const char* b3 = b2 + kstep;
;             if (last && has_next) S.a_ready(nxt);
;             if constexpr (SP2) {
;             PG8_LDB(B0, 0, 0); PG8_LDB(B1, 0, 1); PG8_SCHED; PG8_LDA(At, 0, 0); PG8_STAGE(PG8_SA(1, 1), a1 + hstep, voffA);
;             PG8_WAIT_V(8); PG8_WAIT_L(0); PG8_BAR; PG8_MMA(0, 0, At, B0); PG8_MMA(0, 1, At, B1); PG8_BAR; PG8_SCHED;
;             PG8_LDA(At, 0, 1); PG8_STAGE(PG8_SB(0, 0), b2, voffB); PG8_STAGE(PG8_SB(0, 1), b2 + hstep, voffB); PG8_STAGE(PG8_SA(0, 0), a2, voffA);
;             PG8_WAIT_V(8); PG8_WAIT_L(0); PG8_BAR; PG8_MMA(1, 0, At, B0); PG8_MMA(1, 1, At, B1); PG8_BAR; PG8_SCHED;
.LBB0_111:
	s_add_u32 s26, s60, 0x100
	s_addc_u32 s27, s61, 0
	s_mov_b32 s39, -2
	s_cmp_eq_u32 s73, 1
	s_cbranch_scc1 .Lzero_g4
.Lpeel_g4:
	s_add_u32 s60, s58, 0x100
	s_addc_u32 s61, s59, 0
	s_add_i32 s5, 0, 0x10000
	s_cmp_eq_u32 s39, 40
	s_cselect_b32 s65, s1, s61
	s_cselect_b32 s64, s0, s60
	s_cselect_b32 s63, s57, s27
	s_cselect_b32 s62, s56, s26
	s_add_i32 s8, 0, 0x14000
	v_add_u32_e32 v124, s5, v240
	v_add_u32_e32 v156, s8, v240
	ds_read_b128 v[112:115], v124
	ds_read_b128 v[116:119], v124 offset:1024
	ds_read_b128 v[120:123], v124 offset:2048
	ds_read_b128 v[124:127], v124 offset:3072
	ds_read_b128 v[132:135], v156
	ds_read_b128 v[140:143], v156 offset:1024
	ds_read_b128 v[152:155], v156 offset:2048
	ds_read_b128 v[156:159], v156 offset:3072
	v_lshl_add_u64 v[214:215], s[58:59], 0, v[208:209]
	s_add_i32 m0, s67, 0xc000
	ds_read_b128 v[164:167], v242
	ds_read_b128 v[172:175], v242 offset:1024
	ds_read_b128 v[176:179], v242 offset:2048
	ds_read_b128 v[180:183], v242 offset:3072
	ds_read_b128 v[184:187], v242 offset:4096
	ds_read_b128 v[188:191], v242 offset:5120
	ds_read_b128 v[192:195], v242 offset:6144
	ds_read_b128 v[210:213], v242 offset:7168
	global_load_lds_dwordx4 v[214:215], off
	v_lshl_add_u64 v[214:215], s[58:59], 0, v[206:207]
	s_add_i32 m0, s67, 0xe000
	s_nop 0
	global_load_lds_dwordx4 v[214:215], off
	s_waitcnt vmcnt(32)
	s_waitcnt lgkmcnt(0)
	s_barrier
	s_setprio 1
	s_waitcnt lgkmcnt(0)
	v_mfma_f32_16x16x32_bf16 v[168:171], v[112:115], v[164:167], 0
	v_mfma_f32_16x16x32_bf16 v[160:163], v[120:123], v[164:167], 0
	v_mfma_f32_16x16x32_bf16 v[108:111], v[112:115], v[176:179], 0
	v_mfma_f32_16x16x32_bf16 v[104:107], v[120:123], v[176:179], 0
	v_mfma_f32_16x16x32_bf16 v[92:95], v[112:115], v[184:187], 0
	v_mfma_f32_16x16x32_bf16 v[88:91], v[120:123], v[184:187], 0
	v_mfma_f32_16x16x32_bf16 v[76:79], v[112:115], v[192:195], 0
	v_mfma_f32_16x16x32_bf16 v[72:75], v[120:123], v[192:195], 0
	v_mfma_f32_16x16x32_bf16 v[168:171], v[116:119], v[172:175], v[168:171]
	v_mfma_f32_16x16x32_bf16 v[160:163], v[124:127], v[172:175], v[160:163]
	v_mfma_f32_16x16x32_bf16 v[108:111], v[116:119], v[180:183], v[108:111]
	v_mfma_f32_16x16x32_bf16 v[104:107], v[124:127], v[180:183], v[104:107]
	v_mfma_f32_16x16x32_bf16 v[92:95], v[116:119], v[188:191], v[92:95]
	v_mfma_f32_16x16x32_bf16 v[88:91], v[124:127], v[188:191], v[88:91]
	v_mfma_f32_16x16x32_bf16 v[76:79], v[116:119], v[210:213], v[76:79]
	v_mfma_f32_16x16x32_bf16 v[72:75], v[124:127], v[210:213], v[72:75]
	s_setprio 0
	s_setprio 1
	v_mfma_f32_16x16x32_bf16 v[136:139], v[132:135], v[164:167], 0
	v_mfma_f32_16x16x32_bf16 v[128:131], v[152:155], v[164:167], 0
	v_mfma_f32_16x16x32_bf16 v[100:103], v[132:135], v[176:179], 0
	v_mfma_f32_16x16x32_bf16 v[96:99], v[152:155], v[176:179], 0
	v_mfma_f32_16x16x32_bf16 v[84:87], v[132:135], v[184:187], 0
	v_mfma_f32_16x16x32_bf16 v[80:83], v[152:155], v[184:187], 0
	v_mfma_f32_16x16x32_bf16 v[68:71], v[132:135], v[192:195], 0
	v_mfma_f32_16x16x32_bf16 v[64:67], v[152:155], v[192:195], 0
	v_mfma_f32_16x16x32_bf16 v[136:139], v[140:143], v[172:175], v[136:139]
	v_mfma_f32_16x16x32_bf16 v[128:131], v[156:159], v[172:175], v[128:131]
	v_mfma_f32_16x16x32_bf16 v[100:103], v[140:143], v[180:183], v[100:103]
	v_mfma_f32_16x16x32_bf16 v[96:99], v[156:159], v[180:183], v[96:99]
	v_mfma_f32_16x16x32_bf16 v[84:87], v[140:143], v[188:191], v[84:87]
	v_mfma_f32_16x16x32_bf16 v[80:83], v[156:159], v[188:191], v[80:83]
	v_mfma_f32_16x16x32_bf16 v[68:71], v[140:143], v[210:213], v[68:71]
	v_mfma_f32_16x16x32_bf16 v[64:67], v[156:159], v[210:213], v[64:67]
	s_setprio 0
	s_barrier
	s_add_i32 s5, s5, s66
	v_lshl_add_u64 v[214:215], s[62:63], 0, v[202:203]
	s_mov_b32 m0, s5
	ds_read_b128 v[164:167], v242 offset:16384
	ds_read_b128 v[172:175], v242 offset:17408
	ds_read_b128 v[176:179], v242 offset:18432
	ds_read_b128 v[180:183], v242 offset:19456
	ds_read_b128 v[184:187], v242 offset:20480
	ds_read_b128 v[188:191], v242 offset:21504
	ds_read_b128 v[192:195], v242 offset:22528
	ds_read_b128 v[210:213], v242 offset:23552
	global_load_lds_dwordx4 v[214:215], off
	s_add_i32 m0, s5, 0x2000
	s_add_u32 s20, s62, 0xb0000
	v_lshl_add_u64 v[216:217], s[62:63], 0, v[146:147]
	s_addc_u32 s21, s63, 0
	s_add_i32 s5, s8, s66
	global_load_lds_dwordx4 v[216:217], off
	v_lshl_add_u64 v[218:219], s[20:21], 0, v[202:203]
	s_mov_b32 m0, s5
	v_lshl_add_u64 v[220:221], s[64:65], 0, v[200:201]
	global_load_lds_dwordx4 v[218:219], off
	v_lshl_add_u64 v[218:219], s[20:21], 0, v[146:147]
	s_add_i32 m0, s5, 0x2000
	s_nop 0
	global_load_lds_dwordx4 v[218:219], off
	v_lshl_add_u64 v[218:219], s[64:65], 0, v[204:205]
	s_mov_b32 m0, s67
	s_nop 0
	global_load_lds_dwordx4 v[218:219], off
	s_mov_b32 m0, s68
	s_nop 0
	global_load_lds_dwordx4 v[220:221], off
	s_waitcnt vmcnt(32)
	s_waitcnt lgkmcnt(0)
	s_barrier
	s_setprio 1
	s_waitcnt lgkmcnt(0)
	v_mfma_f32_16x16x32_bf16 v[60:63], v[112:115], v[164:167], 0
	v_mfma_f32_16x16x32_bf16 v[56:59], v[120:123], v[164:167], 0
	v_mfma_f32_16x16x32_bf16 v[44:47], v[112:115], v[176:179], 0
	v_mfma_f32_16x16x32_bf16 v[40:43], v[120:123], v[176:179], 0
	v_mfma_f32_16x16x32_bf16 v[28:31], v[112:115], v[184:187], 0
	v_mfma_f32_16x16x32_bf16 v[24:27], v[120:123], v[184:187], 0
	v_mfma_f32_16x16x32_bf16 v[12:15], v[112:115], v[192:195], 0
	v_mfma_f32_16x16x32_bf16 v[8:11], v[120:123], v[192:195], 0
	v_mfma_f32_16x16x32_bf16 v[60:63], v[116:119], v[172:175], v[60:63]
	v_mfma_f32_16x16x32_bf16 v[56:59], v[124:127], v[172:175], v[56:59]
	v_mfma_f32_16x16x32_bf16 v[44:47], v[116:119], v[180:183], v[44:47]
	v_mfma_f32_16x16x32_bf16 v[40:43], v[124:127], v[180:183], v[40:43]
	v_mfma_f32_16x16x32_bf16 v[28:31], v[116:119], v[188:191], v[28:31]
	v_mfma_f32_16x16x32_bf16 v[24:27], v[124:127], v[188:191], v[24:27]
	v_mfma_f32_16x16x32_bf16 v[12:15], v[116:119], v[210:213], v[12:15]
	v_mfma_f32_16x16x32_bf16 v[8:11], v[124:127], v[210:213], v[8:11]
	s_setprio 0
	s_setprio 1
	v_mfma_f32_16x16x32_bf16 v[52:55], v[132:135], v[164:167], 0
	v_mfma_f32_16x16x32_bf16 v[48:51], v[152:155], v[164:167], 0
	v_mfma_f32_16x16x32_bf16 v[36:39], v[132:135], v[176:179], 0
	v_mfma_f32_16x16x32_bf16 v[32:35], v[152:155], v[176:179], 0
	v_mfma_f32_16x16x32_bf16 v[20:23], v[132:135], v[184:187], 0
	v_mfma_f32_16x16x32_bf16 v[16:19], v[152:155], v[184:187], 0
	v_mfma_f32_16x16x32_bf16 v[4:7], v[132:135], v[192:195], 0
	v_mfma_f32_16x16x32_bf16 v[0:3], v[152:155], v[192:195], 0
	v_mfma_f32_16x16x32_bf16 v[52:55], v[140:143], v[172:175], v[52:55]
	v_mfma_f32_16x16x32_bf16 v[48:51], v[156:159], v[172:175], v[48:51]
	v_mfma_f32_16x16x32_bf16 v[36:39], v[140:143], v[180:183], v[36:39]
	v_mfma_f32_16x16x32_bf16 v[32:35], v[156:159], v[180:183], v[32:35]
	v_mfma_f32_16x16x32_bf16 v[20:23], v[140:143], v[188:191], v[20:23]
	v_mfma_f32_16x16x32_bf16 v[16:19], v[156:159], v[188:191], v[16:19]
	v_mfma_f32_16x16x32_bf16 v[4:7], v[140:143], v[210:213], v[4:7]
	v_mfma_f32_16x16x32_bf16 v[0:3], v[156:159], v[210:213], v[0:3]
	s_setprio 0
	s_barrier
	s_branch .Lmid_g4
; template <class Epi, class Sched, bool ALIGN_EPI = false, bool SP2 = false>
; __device__ __forceinline__ void gemm_phase(PG8_LAS unsigned char* lds, const Gemm g, const Sched& S, const Epi& E) {
;     ...
; #pragma unroll
;         for (int a = 0; a < 2; ++a)
; #pragma unroll
;             for (int b = 0; b < 2; ++b)
; #pragma unroll
;                 for (int m = 0; m < 4; ++m)
; #pragma unroll
;                     for (int n = 0; n < 2; ++n) acc[a][b][m][n] = (f32x4){0.f, 0.f, 0.f, 0.f};
.Lzero_g4:
	v_mov_b32_e32 v0, 0
	v_mov_b32_e32 v1, v0
	v_mov_b32_e32 v2, v0
	v_mov_b32_e32 v3, v0
	v_mov_b32_e32 v4, v0
	v_mov_b32_e32 v5, v0
	v_mov_b32_e32 v6, v0
	v_mov_b32_e32 v7, v0
	v_mov_b32_e32 v16, v0
	v_mov_b32_e32 v17, v0
	v_mov_b32_e32 v18, v0
	v_mov_b32_e32 v19, v0
	v_mov_b32_e32 v20, v0
	v_mov_b32_e32 v21, v0
	v_mov_b32_e32 v22, v0
	v_mov_b32_e32 v23, v0
	v_mov_b32_e32 v32, v0
	v_mov_b32_e32 v33, v0
	v_mov_b32_e32 v34, v0
	v_mov_b32_e32 v35, v0
	v_mov_b32_e32 v36, v0
	v_mov_b32_e32 v37, v0
	v_mov_b32_e32 v38, v0
	v_mov_b32_e32 v39, v0
	v_mov_b32_e32 v48, v0
	v_mov_b32_e32 v49, v0
	v_mov_b32_e32 v50, v0
	v_mov_b32_e32 v51, v0
	v_mov_b32_e32 v52, v0
	v_mov_b32_e32 v53, v0
	v_mov_b32_e32 v54, v0
	v_mov_b32_e32 v55, v0
	v_mov_b32_e32 v8, v0
	v_mov_b32_e32 v9, v0
	v_mov_b32_e32 v10, v0
	v_mov_b32_e32 v11, v0
	v_mov_b32_e32 v12, v0
	v_mov_b32_e32 v13, v0
	v_mov_b32_e32 v14, v0
	v_mov_b32_e32 v15, v0
	v_mov_b32_e32 v24, v0
	v_mov_b32_e32 v25, v0
	v_mov_b32_e32 v26, v0
	v_mov_b32_e32 v27, v0
	v_mov_b32_e32 v28, v0
	v_mov_b32_e32 v29, v0
	v_mov_b32_e32 v30, v0
	v_mov_b32_e32 v31, v0
	v_mov_b32_e32 v40, v0
	v_mov_b32_e32 v41, v0
	v_mov_b32_e32 v42, v0
	v_mov_b32_e32 v43, v0
	v_mov_b32_e32 v44, v0
	v_mov_b32_e32 v45, v0
	v_mov_b32_e32 v46, v0
	v_mov_b32_e32 v47, v0
	v_mov_b32_e32 v56, v0
	v_mov_b32_e32 v57, v0
	v_mov_b32_e32 v58, v0
	v_mov_b32_e32 v59, v0
	v_mov_b32_e32 v60, v0
	v_mov_b32_e32 v61, v0
	v_mov_b32_e32 v62, v0
	v_mov_b32_e32 v63, v0
	v_mov_b32_e32 v64, v0
	v_mov_b32_e32 v65, v0
	v_mov_b32_e32 v66, v0
	v_mov_b32_e32 v67, v0
	v_mov_b32_e32 v68, v0
	v_mov_b32_e32 v69, v0
	v_mov_b32_e32 v70, v0
	v_mov_b32_e32 v71, v0
	v_mov_b32_e32 v80, v0
	v_mov_b32_e32 v81, v0
	v_mov_b32_e32 v82, v0
	v_mov_b32_e32 v83, v0
	v_mov_b32_e32 v84, v0
	v_mov_b32_e32 v85, v0
	v_mov_b32_e32 v86, v0
	v_mov_b32_e32 v87, v0
	v_mov_b32_e32 v96, v0
	v_mov_b32_e32 v97, v0
	v_mov_b32_e32 v98, v0
	v_mov_b32_e32 v99, v0
	v_mov_b32_e32 v100, v0
	v_mov_b32_e32 v101, v0
	v_mov_b32_e32 v102, v0
	v_mov_b32_e32 v103, v0
	v_mov_b32_e32 v128, v0
	v_mov_b32_e32 v129, v0
	v_mov_b32_e32 v130, v0
	v_mov_b32_e32 v131, v0
	v_mov_b32_e32 v136, v0
	v_mov_b32_e32 v137, v0
	v_mov_b32_e32 v138, v0
	v_mov_b32_e32 v139, v0
	v_mov_b32_e32 v72, v0
	v_mov_b32_e32 v73, v0
	v_mov_b32_e32 v74, v0
	v_mov_b32_e32 v75, v0
	v_mov_b32_e32 v76, v0
	v_mov_b32_e32 v77, v0
	v_mov_b32_e32 v78, v0
	v_mov_b32_e32 v79, v0
	v_mov_b32_e32 v88, v0
	v_mov_b32_e32 v89, v0
	v_mov_b32_e32 v90, v0
	v_mov_b32_e32 v91, v0
	v_mov_b32_e32 v92, v0
	v_mov_b32_e32 v93, v0
	v_mov_b32_e32 v94, v0
	v_mov_b32_e32 v95, v0
	v_mov_b32_e32 v104, v0
	v_mov_b32_e32 v105, v0
	v_mov_b32_e32 v106, v0
	v_mov_b32_e32 v107, v0
	v_mov_b32_e32 v108, v0
	v_mov_b32_e32 v109, v0
	v_mov_b32_e32 v110, v0
	v_mov_b32_e32 v111, v0
	v_mov_b32_e32 v160, v0
	v_mov_b32_e32 v161, v0
	v_mov_b32_e32 v162, v0
	v_mov_b32_e32 v163, v0
	v_mov_b32_e32 v168, v0
	v_mov_b32_e32 v169, v0
	v_mov_b32_e32 v170, v0
	v_mov_b32_e32 v171, v0

; #define PG8_STAGE(bufoff, gbase, voff) do { _Pragma("unroll") for (int _i = 0; _i < 2; ++_i) \
;         __builtin_amdgcn_global_load_lds((const unsigned*)((const char*)(gbase) + (voff)[_i]), (PG8_LAS unsigned*)(lds + (bufoff) + ldsw + _i * 8192), 16, 0, 0); } while (0)
; #define PG8_LDA(dst, b, h) do { _Pragma("unroll") for (int m = 0; m < 4; ++m) _Pragma("unroll") for (int k = 0; k < 2; ++k) dst[m][k] = *(const PG8_LAS bf16x8*)(lds + PG8_SA(b, h) + aoff + m * 2048 + k * 1024); } while (0)
; #define PG8_LDB(dst, b, h) do { _Pragma("unroll") for (int n = 0; n < 2; ++n) _Pragma("unroll") for (int k = 0; k < 2; ++k) dst[n][k] = *(const PG8_LAS bf16x8*)(lds + PG8_SB(b, h) + boff + n * 2048 + k * 1024); } while (0)
; #define PG8_MMA(ai, bj, At, Bt) do { __builtin_amdgcn_s_setprio(1); _Pragma("unroll") for (int m = 0; m < 4; ++m) _Pragma("unroll") for (int n = 0; n < 2; ++n) _Pragma("unroll") for (int k = 0; k < 2; ++k) \
;         acc[ai][bj][m][n] = __builtin_amdgcn_mfma_f32_16x16x32_bf16(Bt[n][k], At[m][k], acc[ai][bj][m][n], 0, 0, 0); __builtin_amdgcn_s_setprio(0); } while (0)
; #define PG8_WAIT_V(n) asm volatile("s_waitcnt vmcnt(" #n ")" ::: "memory")
; #define PG8_WAIT_L(n) asm volatile("s_waitcnt lgkmcnt(" #n ")" ::: "memory")
; #define PG8_BAR __builtin_amdgcn_s_barrier()
; #define PG8_SCHED __builtin_amdgcn_sched_barrier(0)
; template <class Epi, class Sched, bool ALIGN_EPI = false, bool SP2 = false>
; __device__ __forceinline__ void gemm_phase(PG8_LAS unsigned char* lds, const Gemm g, const Sched& S, const Epi& E) {
;     ...
;             PG8_LDB(B0, 1, 0); PG8_LDB(B1, 1, 1); PG8_SCHED; PG8_LDA(At, 1, 0); PG8_STAGE(PG8_SA(0, 1), a2 + hstep, voffA);
;             PG8_WAIT_V(8); PG8_WAIT_L(0); PG8_BAR; PG8_MMA(0, 0, At, B0); PG8_MMA(0, 1, At, B1); PG8_BAR; PG8_SCHED;
.Lmid_g4:
	s_add_i32 s5, 0, 0x18000
	s_add_i32 s8, 0, 0x1c000
	v_add_u32_e32 v124, s5, v240
	v_add_u32_e32 v156, s8, v240
	ds_read_b128 v[112:115], v124
	ds_read_b128 v[116:119], v124 offset:1024
	ds_read_b128 v[120:123], v124 offset:2048
	ds_read_b128 v[124:127], v124 offset:3072
	ds_read_b128 v[132:135], v156
	ds_read_b128 v[140:143], v156 offset:1024
	ds_read_b128 v[152:155], v156 offset:2048
	ds_read_b128 v[156:159], v156 offset:3072
	s_add_u32 s20, s64, 0xb0000
	s_addc_u32 s21, s65, 0
	s_mov_b32 m0, s69
	v_lshl_add_u64 v[222:223], s[20:21], 0, v[204:205]
	ds_read_b128 v[164:167], v242 offset:32768
	ds_read_b128 v[172:175], v242 offset:33792
	ds_read_b128 v[176:179], v242 offset:34816
	ds_read_b128 v[180:183], v242 offset:35840
	ds_read_b128 v[184:187], v242 offset:36864
	ds_read_b128 v[188:191], v242 offset:37888
	ds_read_b128 v[192:195], v242 offset:38912
	ds_read_b128 v[210:213], v242 offset:39936
	global_load_lds_dwordx4 v[222:223], off
	v_lshl_add_u64 v[222:223], s[20:21], 0, v[200:201]
	s_mov_b32 m0, s70
	s_nop 0
	global_load_lds_dwordx4 v[222:223], off
	s_waitcnt vmcnt(8)
	s_waitcnt lgkmcnt(0)
	s_barrier
	s_setprio 1
	s_waitcnt lgkmcnt(0)
	v_mfma_f32_16x16x32_bf16 v[168:171], v[112:115], v[164:167], v[168:171]
	v_mfma_f32_16x16x32_bf16 v[160:163], v[120:123], v[164:167], v[160:163]
	v_mfma_f32_16x16x32_bf16 v[108:111], v[112:115], v[176:179], v[108:111]
	v_mfma_f32_16x16x32_bf16 v[104:107], v[120:123], v[176:179], v[104:107]
	v_mfma_f32_16x16x32_bf16 v[92:95], v[112:115], v[184:187], v[92:95]
	v_mfma_f32_16x16x32_bf16 v[88:91], v[120:123], v[184:187], v[88:91]
	v_mfma_f32_16x16x32_bf16 v[76:79], v[112:115], v[192:195], v[76:79]
	v_mfma_f32_16x16x32_bf16 v[72:75], v[120:123], v[192:195], v[72:75]
	v_mfma_f32_16x16x32_bf16 v[168:171], v[116:119], v[172:175], v[168:171]
	v_mfma_f32_16x16x32_bf16 v[160:163], v[124:127], v[172:175], v[160:163]
	v_mfma_f32_16x16x32_bf16 v[108:111], v[116:119], v[180:183], v[108:111]
	v_mfma_f32_16x16x32_bf16 v[104:107], v[124:127], v[180:183], v[104:107]
	v_mfma_f32_16x16x32_bf16 v[92:95], v[116:119], v[188:191], v[92:95]
	v_mfma_f32_16x16x32_bf16 v[88:91], v[124:127], v[188:191], v[88:91]
	v_mfma_f32_16x16x32_bf16 v[76:79], v[116:119], v[210:213], v[76:79]
	v_mfma_f32_16x16x32_bf16 v[72:75], v[124:127], v[210:213], v[72:75]
	s_setprio 0
	s_setprio 1
	v_mfma_f32_16x16x32_bf16 v[136:139], v[132:135], v[164:167], v[136:139]
	v_mfma_f32_16x16x32_bf16 v[128:131], v[152:155], v[164:167], v[128:131]
	v_mfma_f32_16x16x32_bf16 v[100:103], v[132:135], v[176:179], v[100:103]
	v_mfma_f32_16x16x32_bf16 v[96:99], v[152:155], v[176:179], v[96:99]
	v_mfma_f32_16x16x32_bf16 v[84:87], v[132:135], v[184:187], v[84:87]
	v_mfma_f32_16x16x32_bf16 v[80:83], v[152:155], v[184:187], v[80:83]
	v_mfma_f32_16x16x32_bf16 v[68:71], v[132:135], v[192:195], v[68:71]
	v_mfma_f32_16x16x32_bf16 v[64:67], v[152:155], v[192:195], v[64:67]
	v_mfma_f32_16x16x32_bf16 v[136:139], v[140:143], v[172:175], v[136:139]
	v_mfma_f32_16x16x32_bf16 v[128:131], v[156:159], v[172:175], v[128:131]
	v_mfma_f32_16x16x32_bf16 v[100:103], v[140:143], v[180:183], v[100:103]
	v_mfma_f32_16x16x32_bf16 v[96:99], v[156:159], v[180:183], v[96:99]
	v_mfma_f32_16x16x32_bf16 v[84:87], v[140:143], v[188:191], v[84:87]
	v_mfma_f32_16x16x32_bf16 v[80:83], v[156:159], v[188:191], v[80:83]
	v_mfma_f32_16x16x32_bf16 v[68:71], v[140:143], v[210:213], v[68:71]
	v_mfma_f32_16x16x32_bf16 v[64:67], v[156:159], v[210:213], v[64:67]
	s_setprio 0
	s_barrier
; #define PG8_STAGE(bufoff, gbase, voff) do { _Pragma("unroll") for (int _i = 0; _i < 2; ++_i) \
;         __builtin_amdgcn_global_load_lds((const unsigned*)((const char*)(gbase) + (voff)[_i]), (PG8_LAS unsigned*)(lds + (bufoff) + ldsw + _i * 8192), 16, 0, 0); } while (0)
; #define PG8_LDA(dst, b, h) do { _Pragma("unroll") for (int m = 0; m < 4; ++m) _Pragma("unroll") for (int k = 0; k < 2; ++k) dst[m][k] = *(const PG8_LAS bf16x8*)(lds + PG8_SA(b, h) + aoff + m * 2048 + k * 1024); } while (0)
; #define PG8_MMA(ai, bj, At, Bt) do { __builtin_amdgcn_s_setprio(1); _Pragma("unroll") for (int m = 0; m < 4; ++m) _Pragma("unroll") for (int n = 0; n < 2; ++n) _Pragma("unroll") for (int k = 0; k < 2; ++k) \
;         acc[ai][bj][m][n] = __builtin_amdgcn_mfma_f32_16x16x32_bf16(Bt[n][k], At[m][k], acc[ai][bj][m][n], 0, 0, 0); __builtin_amdgcn_s_setprio(0); } while (0)
; #define PG8_WAIT_V(n) asm volatile("s_waitcnt vmcnt(" #n ")" ::: "memory")
; #define PG8_WAIT_L(n) asm volatile("s_waitcnt lgkmcnt(" #n ")" ::: "memory")
; #define PG8_BAR __builtin_amdgcn_s_barrier()
; #define PG8_SCHED __builtin_amdgcn_sched_barrier(0)
; template <class Epi, class Sched, bool ALIGN_EPI = false, bool SP2 = false>
; __device__ __forceinline__ void gemm_phase(PG8_LAS unsigned char* lds, const Gemm g, const Sched& S, const Epi& E) {
;     ...
;         for (int t = 0; t < nt; t += 2) {
;     ...
;             PG8_LDA(At, 1, 1); PG8_STAGE(PG8_SB(1, 0), b3, voffB); PG8_STAGE(PG8_SB(1, 1), b3 + hstep, voffB); PG8_STAGE(PG8_SA(1, 0), a3, voffA);
;             PG8_WAIT_V(8); PG8_WAIT_L(0); PG8_BAR; PG8_MMA(1, 0, At, B0); PG8_MMA(1, 1, At, B1); PG8_BAR; PG8_SCHED;
;     ...
;         if constexpr (ALIGN_EPI) { if (wr == 0) PG8_BAR; }
	s_add_i32 s5, s5, s66
	v_lshl_add_u64 v[214:215], v[214:215], 0, s[22:23]
	s_mov_b32 m0, s5
	ds_read_b128 v[164:167], v242 offset:49152
	ds_read_b128 v[172:175], v242 offset:50176
	ds_read_b128 v[176:179], v242 offset:51200
	ds_read_b128 v[180:183], v242 offset:52224
	ds_read_b128 v[184:187], v242 offset:53248
	ds_read_b128 v[188:191], v242 offset:54272
	ds_read_b128 v[192:195], v242 offset:55296
	ds_read_b128 v[210:213], v242 offset:56320
	global_load_lds_dwordx4 v[214:215], off
	s_add_i32 m0, s5, 0x2000
	s_add_u32 s20, s62, 0xb0080
	v_lshl_add_u64 v[214:215], v[216:217], 0, s[22:23]
	s_addc_u32 s21, s63, 0
	s_add_i32 s5, s8, s66
	global_load_lds_dwordx4 v[214:215], off
	v_lshl_add_u64 v[214:215], s[20:21], 0, v[202:203]
	s_mov_b32 m0, s5
	s_nop 0
	global_load_lds_dwordx4 v[214:215], off
	v_lshl_add_u64 v[214:215], s[20:21], 0, v[146:147]
	s_add_i32 m0, s5, 0x2000
	s_nop 0
	global_load_lds_dwordx4 v[214:215], off
	v_lshl_add_u64 v[214:215], v[218:219], 0, s[22:23]
	s_mov_b32 m0, s71
	s_nop 0
	global_load_lds_dwordx4 v[214:215], off
	v_lshl_add_u64 v[214:215], v[220:221], 0, s[22:23]
	s_mov_b32 m0, s72
	s_nop 0
	global_load_lds_dwordx4 v[214:215], off
	s_waitcnt vmcnt(8)
	s_waitcnt lgkmcnt(0)
	s_barrier
	s_setprio 1
	s_waitcnt lgkmcnt(0)
	v_mfma_f32_16x16x32_bf16 v[60:63], v[112:115], v[164:167], v[60:63]
	v_mfma_f32_16x16x32_bf16 v[56:59], v[120:123], v[164:167], v[56:59]
	v_mfma_f32_16x16x32_bf16 v[44:47], v[112:115], v[176:179], v[44:47]
	v_mfma_f32_16x16x32_bf16 v[40:43], v[120:123], v[176:179], v[40:43]
	v_mfma_f32_16x16x32_bf16 v[28:31], v[112:115], v[184:187], v[28:31]
	v_mfma_f32_16x16x32_bf16 v[24:27], v[120:123], v[184:187], v[24:27]
	v_mfma_f32_16x16x32_bf16 v[12:15], v[112:115], v[192:195], v[12:15]
	v_mfma_f32_16x16x32_bf16 v[8:11], v[120:123], v[192:195], v[8:11]
	v_mfma_f32_16x16x32_bf16 v[60:63], v[116:119], v[172:175], v[60:63]
	v_mfma_f32_16x16x32_bf16 v[56:59], v[124:127], v[172:175], v[56:59]
	v_mfma_f32_16x16x32_bf16 v[44:47], v[116:119], v[180:183], v[44:47]
	v_mfma_f32_16x16x32_bf16 v[40:43], v[124:127], v[180:183], v[40:43]
	v_mfma_f32_16x16x32_bf16 v[28:31], v[116:119], v[188:191], v[28:31]
	v_mfma_f32_16x16x32_bf16 v[24:27], v[124:127], v[188:191], v[24:27]
	v_mfma_f32_16x16x32_bf16 v[12:15], v[116:119], v[210:213], v[12:15]
	v_mfma_f32_16x16x32_bf16 v[8:11], v[124:127], v[210:213], v[8:11]
	s_setprio 0
	s_setprio 1
	v_mfma_f32_16x16x32_bf16 v[52:55], v[132:135], v[164:167], v[52:55]
	v_mfma_f32_16x16x32_bf16 v[48:51], v[152:155], v[164:167], v[48:51]
	v_mfma_f32_16x16x32_bf16 v[36:39], v[132:135], v[176:179], v[36:39]
	v_mfma_f32_16x16x32_bf16 v[32:35], v[152:155], v[176:179], v[32:35]
	v_mfma_f32_16x16x32_bf16 v[20:23], v[132:135], v[184:187], v[20:23]
	v_mfma_f32_16x16x32_bf16 v[16:19], v[152:155], v[184:187], v[16:19]
	v_mfma_f32_16x16x32_bf16 v[4:7], v[132:135], v[192:195], v[4:7]
	v_mfma_f32_16x16x32_bf16 v[0:3], v[152:155], v[192:195], v[0:3]
	v_mfma_f32_16x16x32_bf16 v[52:55], v[140:143], v[172:175], v[52:55]
	v_mfma_f32_16x16x32_bf16 v[48:51], v[156:159], v[172:175], v[48:51]
	v_mfma_f32_16x16x32_bf16 v[36:39], v[140:143], v[180:183], v[36:39]
	v_mfma_f32_16x16x32_bf16 v[32:35], v[156:159], v[180:183], v[32:35]
	v_mfma_f32_16x16x32_bf16 v[20:23], v[140:143], v[188:191], v[20:23]
	v_mfma_f32_16x16x32_bf16 v[16:19], v[156:159], v[188:191], v[16:19]
	v_mfma_f32_16x16x32_bf16 v[4:7], v[140:143], v[210:213], v[4:7]
	v_mfma_f32_16x16x32_bf16 v[0:3], v[156:159], v[210:213], v[0:3]
	s_setprio 0
	s_barrier
	s_add_i32 s39, s39, 2
	s_add_u32 s26, s26, 0x100
	s_addc_u32 s27, s27, 0
	s_cmp_gt_u32 s39, 41
	s_mov_b64 s[58:59], s[60:61]
	s_cbranch_scc0 .LBB0_112
	s_and_b64 vcc, exec, s[54:55]
	s_cbranch_vccz .LBB0_115
	s_barrier

;     __device__ __forceinline__ void prefetch(Pre& p, const Unit& u, int wr, int fr, int fq) const { prefetch_ss(p, ss, u, wr, fr, fq); }
;     __device__ __forceinline__ void prefetch(Pre& p, const Unit& u, int wr, int fr, int fq) const { prefetch_ss(p, ss, u, wr, fr, fq); }
;     __device__ __forceinline__ void prefetch(Pre& p, const Unit& u, int wr, int fr, int fq) const { prefetch_ss(p, ss, u, wr, fr, fq); }
; template <class Epi, class Sched, bool ALIGN_EPI = false, bool SP2 = false>
; __device__ __forceinline__ void gemm_phase(PG8_LAS unsigned char* lds, const Gemm g, const Sched& S, const Epi& E) {
;     ...
;         const bool has_next = S.next(ui + 1, nxt);
;         typename Epi::Pre pre; E.prefetch(pre, cur, wr, fr, fq);
;         const char* nA = has_next ? (const char*)g.A + (size_t)nxt.pm * tstep : cA; const char* nB = has_next ? (const char*)g.Bt + (size_t)nxt.pn * tstep : cB;
;         for (int t = 0; t < nt; t += 2) {
;             const bool last = (t == nt - 2);
;             const char* a1 = cA + (size_t)(t + 1) * kstep;
;             const char* a2 = last ? nA : cA + (size_t)(t + 2) * kstep; const char* b2 = last ? nB : cB + (size_t)(t + 2) * kstep;
;             const char* a3 = a2 + kstep; const char* b3 = b2 + kstep;
;             if (last && has_next) S.a_ready(nxt);
.LBB0_151:
	v_lshl_add_u32 v142, s50, 8, v155
	v_ashrrev_i32_e32 v143, 31, v142
	v_lshl_add_u64 v[0:1], v[142:143], 3, v[136:137]
	global_load_dwordx2 v[152:153], v[0:1], off
	global_load_dwordx2 v[146:147], v[0:1], off offset:128
	s_mov_b32 s50, s8
	s_ashr_i32 s51, s8, 31
	s_lshl_b64 s[20:21], s[50:51], 19
	s_add_u32 s54, s28, s20
	s_addc_u32 s55, s29, s21
	s_and_b64 s[20:21], s[40:41], exec
	s_cselect_b32 s26, s55, s61
	s_cselect_b32 s27, s54, s60
	s_ashr_i32 s53, s52, 31
	s_lshl_b64 s[20:21], s[52:53], 19
	s_add_u32 s56, s2, s20
	s_addc_u32 s57, s35, s21
	s_and_b64 s[20:21], s[40:41], exec
	s_cselect_b32 s36, s57, s59
	s_cselect_b32 s39, s56, s58
	s_add_u32 s51, s58, 0x100
	s_addc_u32 s53, s59, 0
	s_add_u32 s58, s60, 0x40080
	s_addc_u32 s59, s61, 0
	s_mov_b32 s72, -2
	s_cmp_eq_u32 s71, 1
	s_cbranch_scc1 .Lzero_g3
; #define PG8_STAGE(bufoff, gbase, voff) do { _Pragma("unroll") for (int _i = 0; _i < 2; ++_i) \
;         __builtin_amdgcn_global_load_lds((const unsigned*)((const char*)(gbase) + (voff)[_i]), (PG8_LAS unsigned*)(lds + (bufoff) + ldsw + _i * 8192), 16, 0, 0); } while (0)
; #define PG8_LDA(dst, b, h) do { _Pragma("unroll") for (int m = 0; m < 4; ++m) _Pragma("unroll") for (int k = 0; k < 2; ++k) dst[m][k] = *(const PG8_LAS bf16x8*)(lds + PG8_SA(b, h) + aoff + m * 2048 + k * 1024); } while (0)
; #define PG8_LDB(dst, b, h) do { _Pragma("unroll") for (int n = 0; n < 2; ++n) _Pragma("unroll") for (int k = 0; k < 2; ++k) dst[n][k] = *(const PG8_LAS bf16x8*)(lds + PG8_SB(b, h) + boff + n * 2048 + k * 1024); } while (0)
; #define PG8_MMA(ai, bj, At, Bt) do { __builtin_amdgcn_s_setprio(1); _Pragma("unroll") for (int m = 0; m < 4; ++m) _Pragma("unroll") for (int n = 0; n < 2; ++n) _Pragma("unroll") for (int k = 0; k < 2; ++k) \
;         acc[ai][bj][m][n] = __builtin_amdgcn_mfma_f32_16x16x32_bf16(Bt[n][k], At[m][k], acc[ai][bj][m][n], 0, 0, 0); __builtin_amdgcn_s_setprio(0); } while (0)
; #define PG8_WAIT_V(n) asm volatile("s_waitcnt vmcnt(" #n ")" ::: "memory")
; #define PG8_WAIT_L(n) asm volatile("s_waitcnt lgkmcnt(" #n ")" ::: "memory")
; #define PG8_BAR __builtin_amdgcn_s_barrier()
; #define PG8_SCHED __builtin_amdgcn_sched_barrier(0)
; template <class Epi, class Sched, bool ALIGN_EPI = false, bool SP2 = false>
; __device__ __forceinline__ void gemm_phase(PG8_LAS unsigned char* lds, const Gemm g, const Sched& S, const Epi& E) {
;     ...
;             PG8_LDB(B0, 0, 0); PG8_LDB(B1, 0, 1); PG8_SCHED; PG8_LDA(At, 0, 0); PG8_STAGE(PG8_SA(1, 1), a1 + hstep, voffA);
;             PG8_WAIT_V(8); PG8_WAIT_L(0); PG8_BAR; PG8_MMA(0, 0, At, B0); PG8_MMA(0, 1, At, B1); PG8_BAR; PG8_SCHED;
;             PG8_LDA(At, 0, 1); PG8_STAGE(PG8_SB(0, 0), b2, voffB); PG8_STAGE(PG8_SB(0, 1), b2 + hstep, voffB); PG8_STAGE(PG8_SA(0, 0), a2, voffA);
;             PG8_WAIT_V(8); PG8_WAIT_L(0); PG8_BAR; PG8_MMA(1, 0, At, B0); PG8_MMA(1, 1, At, B1); PG8_BAR; PG8_SCHED;
.Lpeel_g3:
	s_add_u32 s5, s58, 0xfffc0080
	s_addc_u32 s8, s59, -1
	s_add_i32 s10, 0, 0x10000
	s_cmp_eq_u32 s72, 12
	s_cselect_b32 s63, s26, s8
	s_cselect_b32 s62, s27, s5
	v_add_u32_e32 v143, s10, v157
	s_cselect_b32 s61, s36, s53
	s_cselect_b32 s60, s39, s51
	s_add_i32 s5, 0, 0x14000
	ds_read_b128 v[162:165], v143
	ds_read_b128 v[166:169], v143 offset:1024
	ds_read_b128 v[170:173], v143 offset:2048
	ds_read_b128 v[174:177], v143 offset:3072
	v_add_u32_e32 v143, s5, v157
	ds_read_b128 v[178:181], v143
	ds_read_b128 v[182:185], v143 offset:1024
	ds_read_b128 v[186:189], v143 offset:2048
	ds_read_b128 v[190:193], v143 offset:3072
	v_lshl_add_u64 v[194:195], s[58:59], 0, v[140:141]
	s_add_i32 m0, s65, 0xc000
	ds_read_b128 v[200:203], v161
	ds_read_b128 v[204:207], v161 offset:1024
	ds_read_b128 v[208:211], v161 offset:2048
	ds_read_b128 v[212:215], v161 offset:3072
	ds_read_b128 v[216:219], v161 offset:4096
	ds_read_b128 v[220:223], v161 offset:5120
	ds_read_b128 v[224:227], v161 offset:6144
	ds_read_b128 v[228:231], v161 offset:7168
	global_load_lds_dwordx4 v[194:195], off
	v_lshl_add_u64 v[194:195], s[58:59], 0, v[138:139]
	s_add_i32 m0, s65, 0xe000
	s_nop 0
	global_load_lds_dwordx4 v[194:195], off
	s_waitcnt vmcnt(18)
	s_waitcnt lgkmcnt(0)
	s_barrier
	s_setprio 1
	s_waitcnt lgkmcnt(0)
	v_mfma_f32_16x16x32_bf16 v[124:127], v[162:165], v[200:203], 0
	v_mfma_f32_16x16x32_bf16 v[120:123], v[170:173], v[200:203], 0
	v_mfma_f32_16x16x32_bf16 v[108:111], v[162:165], v[208:211], 0
	v_mfma_f32_16x16x32_bf16 v[104:107], v[170:173], v[208:211], 0
	v_mfma_f32_16x16x32_bf16 v[92:95], v[162:165], v[216:219], 0
	v_mfma_f32_16x16x32_bf16 v[88:91], v[170:173], v[216:219], 0
	v_mfma_f32_16x16x32_bf16 v[76:79], v[162:165], v[224:227], 0
	v_mfma_f32_16x16x32_bf16 v[72:75], v[170:173], v[224:227], 0
	v_mfma_f32_16x16x32_bf16 v[124:127], v[166:169], v[204:207], v[124:127]
	v_mfma_f32_16x16x32_bf16 v[120:123], v[174:177], v[204:207], v[120:123]
	v_mfma_f32_16x16x32_bf16 v[108:111], v[166:169], v[212:215], v[108:111]
	v_mfma_f32_16x16x32_bf16 v[104:107], v[174:177], v[212:215], v[104:107]
	v_mfma_f32_16x16x32_bf16 v[92:95], v[166:169], v[220:223], v[92:95]
	v_mfma_f32_16x16x32_bf16 v[88:91], v[174:177], v[220:223], v[88:91]
	v_mfma_f32_16x16x32_bf16 v[76:79], v[166:169], v[228:231], v[76:79]
	v_mfma_f32_16x16x32_bf16 v[72:75], v[174:177], v[228:231], v[72:75]
	s_setprio 0
	s_setprio 1
	v_mfma_f32_16x16x32_bf16 v[116:119], v[178:181], v[200:203], 0
	v_mfma_f32_16x16x32_bf16 v[112:115], v[186:189], v[200:203], 0
	v_mfma_f32_16x16x32_bf16 v[100:103], v[178:181], v[208:211], 0
	v_mfma_f32_16x16x32_bf16 v[96:99], v[186:189], v[208:211], 0
	v_mfma_f32_16x16x32_bf16 v[84:87], v[178:181], v[216:219], 0
	v_mfma_f32_16x16x32_bf16 v[80:83], v[186:189], v[216:219], 0
	v_mfma_f32_16x16x32_bf16 v[68:71], v[178:181], v[224:227], 0
	v_mfma_f32_16x16x32_bf16 v[64:67], v[186:189], v[224:227], 0
	v_mfma_f32_16x16x32_bf16 v[116:119], v[182:185], v[204:207], v[116:119]
	v_mfma_f32_16x16x32_bf16 v[112:115], v[190:193], v[204:207], v[112:115]
	v_mfma_f32_16x16x32_bf16 v[100:103], v[182:185], v[212:215], v[100:103]
	v_mfma_f32_16x16x32_bf16 v[96:99], v[190:193], v[212:215], v[96:99]
	v_mfma_f32_16x16x32_bf16 v[84:87], v[182:185], v[220:223], v[84:87]
	v_mfma_f32_16x16x32_bf16 v[80:83], v[190:193], v[220:223], v[80:83]
	v_mfma_f32_16x16x32_bf16 v[68:71], v[182:185], v[228:231], v[68:71]
	v_mfma_f32_16x16x32_bf16 v[64:67], v[190:193], v[228:231], v[64:67]
	s_setprio 0
	s_barrier
	s_add_i32 s8, s10, s64
	v_lshl_add_u64 v[194:195], s[60:61], 0, v[132:133]
	s_mov_b32 m0, s8
	ds_read_b128 v[200:203], v161 offset:16384
	ds_read_b128 v[204:207], v161 offset:17408
	ds_read_b128 v[208:211], v161 offset:18432
	ds_read_b128 v[212:215], v161 offset:19456
	ds_read_b128 v[216:219], v161 offset:20480
	ds_read_b128 v[220:223], v161 offset:21504
	ds_read_b128 v[224:227], v161 offset:22528
	ds_read_b128 v[228:231], v161 offset:23552
	global_load_lds_dwordx4 v[194:195], off
	s_add_i32 m0, s8, 0x2000
	s_add_u32 s20, s60, 0x40000
	v_lshl_add_u64 v[240:241], s[60:61], 0, v[128:129]
	s_addc_u32 s21, s61, 0
	s_add_i32 s5, s5, s64
	global_load_lds_dwordx4 v[240:241], off
	v_lshl_add_u64 v[242:243], s[20:21], 0, v[132:133]
	s_mov_b32 m0, s5
	v_lshl_add_u64 v[244:245], s[62:63], 0, v[130:131]
	global_load_lds_dwordx4 v[242:243], off
	v_lshl_add_u64 v[242:243], s[20:21], 0, v[128:129]
	s_add_i32 m0, s5, 0x2000
	s_nop 0
	global_load_lds_dwordx4 v[242:243], off
	v_lshl_add_u64 v[242:243], s[62:63], 0, v[134:135]
	s_mov_b32 m0, s65
	s_nop 0
	global_load_lds_dwordx4 v[242:243], off
	s_mov_b32 m0, s66
	s_nop 0
	global_load_lds_dwordx4 v[244:245], off
	s_waitcnt vmcnt(18)
	s_waitcnt lgkmcnt(0)
	s_barrier
	s_setprio 1
	s_waitcnt lgkmcnt(0)
	v_mfma_f32_16x16x32_bf16 v[60:63], v[162:165], v[200:203], 0
	v_mfma_f32_16x16x32_bf16 v[56:59], v[170:173], v[200:203], 0
	v_mfma_f32_16x16x32_bf16 v[44:47], v[162:165], v[208:211], 0
	v_mfma_f32_16x16x32_bf16 v[40:43], v[170:173], v[208:211], 0
	v_mfma_f32_16x16x32_bf16 v[28:31], v[162:165], v[216:219], 0
	v_mfma_f32_16x16x32_bf16 v[24:27], v[170:173], v[216:219], 0
	v_mfma_f32_16x16x32_bf16 v[12:15], v[162:165], v[224:227], 0
	v_mfma_f32_16x16x32_bf16 v[8:11], v[170:173], v[224:227], 0
	v_mfma_f32_16x16x32_bf16 v[60:63], v[166:169], v[204:207], v[60:63]
	v_mfma_f32_16x16x32_bf16 v[56:59], v[174:177], v[204:207], v[56:59]
	v_mfma_f32_16x16x32_bf16 v[44:47], v[166:169], v[212:215], v[44:47]
	v_mfma_f32_16x16x32_bf16 v[40:43], v[174:177], v[212:215], v[40:43]
	v_mfma_f32_16x16x32_bf16 v[28:31], v[166:169], v[220:223], v[28:31]
	v_mfma_f32_16x16x32_bf16 v[24:27], v[174:177], v[220:223], v[24:27]
	v_mfma_f32_16x16x32_bf16 v[12:15], v[166:169], v[228:231], v[12:15]
	v_mfma_f32_16x16x32_bf16 v[8:11], v[174:177], v[228:231], v[8:11]
	s_setprio 0
	s_setprio 1
	v_mfma_f32_16x16x32_bf16 v[52:55], v[178:181], v[200:203], 0
	v_mfma_f32_16x16x32_bf16 v[48:51], v[186:189], v[200:203], 0
	v_mfma_f32_16x16x32_bf16 v[36:39], v[178:181], v[208:211], 0
	v_mfma_f32_16x16x32_bf16 v[32:35], v[186:189], v[208:211], 0
	v_mfma_f32_16x16x32_bf16 v[20:23], v[178:181], v[216:219], 0
	v_mfma_f32_16x16x32_bf16 v[16:19], v[186:189], v[216:219], 0
	v_mfma_f32_16x16x32_bf16 v[4:7], v[178:181], v[224:227], 0
	v_mfma_f32_16x16x32_bf16 v[0:3], v[186:189], v[224:227], 0
	v_mfma_f32_16x16x32_bf16 v[52:55], v[182:185], v[204:207], v[52:55]
	v_mfma_f32_16x16x32_bf16 v[48:51], v[190:193], v[204:207], v[48:51]
	v_mfma_f32_16x16x32_bf16 v[36:39], v[182:185], v[212:215], v[36:39]
	v_mfma_f32_16x16x32_bf16 v[32:35], v[190:193], v[212:215], v[32:35]
	v_mfma_f32_16x16x32_bf16 v[20:23], v[182:185], v[220:223], v[20:23]
	v_mfma_f32_16x16x32_bf16 v[16:19], v[190:193], v[220:223], v[16:19]
	v_mfma_f32_16x16x32_bf16 v[4:7], v[182:185], v[228:231], v[4:7]
	v_mfma_f32_16x16x32_bf16 v[0:3], v[190:193], v[228:231], v[0:3]
	s_setprio 0
	s_barrier
	s_branch .Lmid_g3

; #define PG8_STAGE(bufoff, gbase, voff) do { _Pragma("unroll") for (int _i = 0; _i < 2; ++_i) \
;         __builtin_amdgcn_global_load_lds((const unsigned*)((const char*)(gbase) + (voff)[_i]), (PG8_LAS unsigned*)(lds + (bufoff) + ldsw + _i * 8192), 16, 0, 0); } while (0)
; #define PG8_LDA(dst, b, h) do { _Pragma("unroll") for (int m = 0; m < 4; ++m) _Pragma("unroll") for (int k = 0; k < 2; ++k) dst[m][k] = *(const PG8_LAS bf16x8*)(lds + PG8_SA(b, h) + aoff + m * 2048 + k * 1024); } while (0)
; #define PG8_LDB(dst, b, h) do { _Pragma("unroll") for (int n = 0; n < 2; ++n) _Pragma("unroll") for (int k = 0; k < 2; ++k) dst[n][k] = *(const PG8_LAS bf16x8*)(lds + PG8_SB(b, h) + boff + n * 2048 + k * 1024); } while (0)
; #define PG8_MMA(ai, bj, At, Bt) do { __builtin_amdgcn_s_setprio(1); _Pragma("unroll") for (int m = 0; m < 4; ++m) _Pragma("unroll") for (int n = 0; n < 2; ++n) _Pragma("unroll") for (int k = 0; k < 2; ++k) \
;         acc[ai][bj][m][n] = __builtin_amdgcn_mfma_f32_16x16x32_bf16(Bt[n][k], At[m][k], acc[ai][bj][m][n], 0, 0, 0); __builtin_amdgcn_s_setprio(0); } while (0)
; #define PG8_WAIT_V(n) asm volatile("s_waitcnt vmcnt(" #n ")" ::: "memory")
; #define PG8_WAIT_L(n) asm volatile("s_waitcnt lgkmcnt(" #n ")" ::: "memory")
; #define PG8_BAR __builtin_amdgcn_s_barrier()
; #define PG8_SCHED __builtin_amdgcn_sched_barrier(0)
; template <class Epi, class Sched, bool ALIGN_EPI = false, bool SP2 = false>
; __device__ __forceinline__ void gemm_phase(PG8_LAS unsigned char* lds, const Gemm g, const Sched& S, const Epi& E) {
;     ...
;             PG8_LDB(B0, 1, 0); PG8_LDB(B1, 1, 1); PG8_SCHED; PG8_LDA(At, 1, 0); PG8_STAGE(PG8_SA(0, 1), a2 + hstep, voffA);
;             PG8_WAIT_V(8); PG8_WAIT_L(0); PG8_BAR; PG8_MMA(0, 0, At, B0); PG8_MMA(0, 1, At, B1); PG8_BAR; PG8_SCHED;
.Lmid_g3:
	s_add_i32 s5, 0, 0x18000
	v_add_u32_e32 v143, s5, v157
	s_add_i32 s8, 0, 0x1c000
	ds_read_b128 v[162:165], v143
	ds_read_b128 v[166:169], v143 offset:1024
	ds_read_b128 v[170:173], v143 offset:2048
	ds_read_b128 v[174:177], v143 offset:3072
	v_add_u32_e32 v143, s8, v157
	ds_read_b128 v[178:181], v143
	ds_read_b128 v[182:185], v143 offset:1024
	ds_read_b128 v[186:189], v143 offset:2048
	ds_read_b128 v[190:193], v143 offset:3072
	s_add_u32 s20, s62, 0x40000
	s_addc_u32 s21, s63, 0
	s_mov_b32 m0, s67
	v_lshl_add_u64 v[246:247], s[20:21], 0, v[134:135]
	ds_read_b128 v[200:203], v161 offset:32768
	ds_read_b128 v[204:207], v161 offset:33792
	ds_read_b128 v[208:211], v161 offset:34816
	ds_read_b128 v[212:215], v161 offset:35840
	ds_read_b128 v[216:219], v161 offset:36864
	ds_read_b128 v[220:223], v161 offset:37888
	ds_read_b128 v[224:227], v161 offset:38912
	ds_read_b128 v[228:231], v161 offset:39936
	global_load_lds_dwordx4 v[246:247], off
	v_lshl_add_u64 v[246:247], s[20:21], 0, v[130:131]
	s_mov_b32 m0, s68
	s_nop 0
	global_load_lds_dwordx4 v[246:247], off
	s_waitcnt vmcnt(8)
	s_waitcnt lgkmcnt(0)
	s_barrier
	s_setprio 1
	s_waitcnt lgkmcnt(0)
	v_mfma_f32_16x16x32_bf16 v[124:127], v[162:165], v[200:203], v[124:127]
	v_mfma_f32_16x16x32_bf16 v[120:123], v[170:173], v[200:203], v[120:123]
	v_mfma_f32_16x16x32_bf16 v[108:111], v[162:165], v[208:211], v[108:111]
	v_mfma_f32_16x16x32_bf16 v[104:107], v[170:173], v[208:211], v[104:107]
	v_mfma_f32_16x16x32_bf16 v[92:95], v[162:165], v[216:219], v[92:95]
	v_mfma_f32_16x16x32_bf16 v[88:91], v[170:173], v[216:219], v[88:91]
	v_mfma_f32_16x16x32_bf16 v[76:79], v[162:165], v[224:227], v[76:79]
	v_mfma_f32_16x16x32_bf16 v[72:75], v[170:173], v[224:227], v[72:75]
	v_mfma_f32_16x16x32_bf16 v[124:127], v[166:169], v[204:207], v[124:127]
	v_mfma_f32_16x16x32_bf16 v[120:123], v[174:177], v[204:207], v[120:123]
	v_mfma_f32_16x16x32_bf16 v[108:111], v[166:169], v[212:215], v[108:111]
	v_mfma_f32_16x16x32_bf16 v[104:107], v[174:177], v[212:215], v[104:107]
	v_mfma_f32_16x16x32_bf16 v[92:95], v[166:169], v[220:223], v[92:95]
	v_mfma_f32_16x16x32_bf16 v[88:91], v[174:177], v[220:223], v[88:91]
	v_mfma_f32_16x16x32_bf16 v[76:79], v[166:169], v[228:231], v[76:79]
	v_mfma_f32_16x16x32_bf16 v[72:75], v[174:177], v[228:231], v[72:75]
	s_setprio 0
	s_setprio 1
	v_mfma_f32_16x16x32_bf16 v[116:119], v[178:181], v[200:203], v[116:119]
	v_mfma_f32_16x16x32_bf16 v[112:115], v[186:189], v[200:203], v[112:115]
	v_mfma_f32_16x16x32_bf16 v[100:103], v[178:181], v[208:211], v[100:103]
	v_mfma_f32_16x16x32_bf16 v[96:99], v[186:189], v[208:211], v[96:99]
	v_mfma_f32_16x16x32_bf16 v[84:87], v[178:181], v[216:219], v[84:87]
	v_mfma_f32_16x16x32_bf16 v[80:83], v[186:189], v[216:219], v[80:83]
	v_mfma_f32_16x16x32_bf16 v[68:71], v[178:181], v[224:227], v[68:71]
	v_mfma_f32_16x16x32_bf16 v[64:67], v[186:189], v[224:227], v[64:67]
	v_mfma_f32_16x16x32_bf16 v[116:119], v[182:185], v[204:207], v[116:119]
	v_mfma_f32_16x16x32_bf16 v[112:115], v[190:193], v[204:207], v[112:115]
	v_mfma_f32_16x16x32_bf16 v[100:103], v[182:185], v[212:215], v[100:103]
	v_mfma_f32_16x16x32_bf16 v[96:99], v[190:193], v[212:215], v[96:99]
	v_mfma_f32_16x16x32_bf16 v[84:87], v[182:185], v[220:223], v[84:87]
	v_mfma_f32_16x16x32_bf16 v[80:83], v[190:193], v[220:223], v[80:83]
	v_mfma_f32_16x16x32_bf16 v[68:71], v[182:185], v[228:231], v[68:71]
	v_mfma_f32_16x16x32_bf16 v[64:67], v[190:193], v[228:231], v[64:67]
	s_setprio 0
	s_barrier
; #define PG8_STAGE(bufoff, gbase, voff) do { _Pragma("unroll") for (int _i = 0; _i < 2; ++_i) \
;         __builtin_amdgcn_global_load_lds((const unsigned*)((const char*)(gbase) + (voff)[_i]), (PG8_LAS unsigned*)(lds + (bufoff) + ldsw + _i * 8192), 16, 0, 0); } while (0)
; #define PG8_LDA(dst, b, h) do { _Pragma("unroll") for (int m = 0; m < 4; ++m) _Pragma("unroll") for (int k = 0; k < 2; ++k) dst[m][k] = *(const PG8_LAS bf16x8*)(lds + PG8_SA(b, h) + aoff + m * 2048 + k * 1024); } while (0)
; #define PG8_MMA(ai, bj, At, Bt) do { __builtin_amdgcn_s_setprio(1); _Pragma("unroll") for (int m = 0; m < 4; ++m) _Pragma("unroll") for (int n = 0; n < 2; ++n) _Pragma("unroll") for (int k = 0; k < 2; ++k) \
;         acc[ai][bj][m][n] = __builtin_amdgcn_mfma_f32_16x16x32_bf16(Bt[n][k], At[m][k], acc[ai][bj][m][n], 0, 0, 0); __builtin_amdgcn_s_setprio(0); } while (0)
; #define PG8_WAIT_V(n) asm volatile("s_waitcnt vmcnt(" #n ")" ::: "memory")
; #define PG8_WAIT_L(n) asm volatile("s_waitcnt lgkmcnt(" #n ")" ::: "memory")
; #define PG8_BAR __builtin_amdgcn_s_barrier()
; #define PG8_SCHED __builtin_amdgcn_sched_barrier(0)
; template <class Epi, class Sched, bool ALIGN_EPI = false, bool SP2 = false>
; __device__ __forceinline__ void gemm_phase(PG8_LAS unsigned char* lds, const Gemm g, const Sched& S, const Epi& E) {
;     ...
;         for (int t = 0; t < nt; t += 2) {
;     ...
;             PG8_LDA(At, 1, 1); PG8_STAGE(PG8_SB(1, 0), b3, voffB); PG8_STAGE(PG8_SB(1, 1), b3 + hstep, voffB); PG8_STAGE(PG8_SA(1, 0), a3, voffA);
;             PG8_WAIT_V(8); PG8_WAIT_L(0); PG8_BAR; PG8_MMA(1, 0, At, B0); PG8_MMA(1, 1, At, B1); PG8_BAR; PG8_SCHED;
;     ...
;         if constexpr (ALIGN_EPI) { if (wr == 0) PG8_BAR; }
	s_add_i32 s5, s5, s64
	v_lshl_add_u64 v[194:195], v[194:195], 0, s[22:23]
	s_mov_b32 m0, s5
	ds_read_b128 v[200:203], v161 offset:49152
	ds_read_b128 v[204:207], v161 offset:50176
	ds_read_b128 v[208:211], v161 offset:51200
	ds_read_b128 v[212:215], v161 offset:52224
	ds_read_b128 v[216:219], v161 offset:53248
	ds_read_b128 v[220:223], v161 offset:54272
	ds_read_b128 v[224:227], v161 offset:55296
	ds_read_b128 v[228:231], v161 offset:56320
	global_load_lds_dwordx4 v[194:195], off
	s_add_i32 m0, s5, 0x2000
	s_add_u32 s20, s60, 0x40080
	v_lshl_add_u64 v[194:195], v[240:241], 0, s[22:23]
	s_addc_u32 s21, s61, 0
	s_add_i32 s5, s8, s64
	global_load_lds_dwordx4 v[194:195], off
	v_lshl_add_u64 v[194:195], s[20:21], 0, v[132:133]
	s_mov_b32 m0, s5
	s_nop 0
	global_load_lds_dwordx4 v[194:195], off
	v_lshl_add_u64 v[194:195], s[20:21], 0, v[128:129]
	s_add_i32 m0, s5, 0x2000
	s_nop 0
	global_load_lds_dwordx4 v[194:195], off
	v_lshl_add_u64 v[194:195], v[242:243], 0, s[22:23]
	s_mov_b32 m0, s69
	s_nop 0
	global_load_lds_dwordx4 v[194:195], off
	v_lshl_add_u64 v[194:195], v[244:245], 0, s[22:23]
	s_mov_b32 m0, s70
	s_nop 0
	global_load_lds_dwordx4 v[194:195], off
	s_waitcnt vmcnt(8)
	s_waitcnt lgkmcnt(0)
	s_barrier
	s_setprio 1
	s_waitcnt lgkmcnt(0)
	v_mfma_f32_16x16x32_bf16 v[60:63], v[162:165], v[200:203], v[60:63]
	v_mfma_f32_16x16x32_bf16 v[56:59], v[170:173], v[200:203], v[56:59]
	v_mfma_f32_16x16x32_bf16 v[44:47], v[162:165], v[208:211], v[44:47]
	v_mfma_f32_16x16x32_bf16 v[40:43], v[170:173], v[208:211], v[40:43]
	v_mfma_f32_16x16x32_bf16 v[28:31], v[162:165], v[216:219], v[28:31]
	v_mfma_f32_16x16x32_bf16 v[24:27], v[170:173], v[216:219], v[24:27]
	v_mfma_f32_16x16x32_bf16 v[12:15], v[162:165], v[224:227], v[12:15]
	v_mfma_f32_16x16x32_bf16 v[8:11], v[170:173], v[224:227], v[8:11]
	v_mfma_f32_16x16x32_bf16 v[60:63], v[166:169], v[204:207], v[60:63]
	v_mfma_f32_16x16x32_bf16 v[56:59], v[174:177], v[204:207], v[56:59]
	v_mfma_f32_16x16x32_bf16 v[44:47], v[166:169], v[212:215], v[44:47]
	v_mfma_f32_16x16x32_bf16 v[40:43], v[174:177], v[212:215], v[40:43]
	v_mfma_f32_16x16x32_bf16 v[28:31], v[166:169], v[220:223], v[28:31]
	v_mfma_f32_16x16x32_bf16 v[24:27], v[174:177], v[220:223], v[24:27]
	v_mfma_f32_16x16x32_bf16 v[12:15], v[166:169], v[228:231], v[12:15]
	v_mfma_f32_16x16x32_bf16 v[8:11], v[174:177], v[228:231], v[8:11]
	s_setprio 0
	s_setprio 1
	v_mfma_f32_16x16x32_bf16 v[52:55], v[178:181], v[200:203], v[52:55]
	v_mfma_f32_16x16x32_bf16 v[48:51], v[186:189], v[200:203], v[48:51]
	v_mfma_f32_16x16x32_bf16 v[36:39], v[178:181], v[208:211], v[36:39]
	v_mfma_f32_16x16x32_bf16 v[32:35], v[186:189], v[208:211], v[32:35]
	v_mfma_f32_16x16x32_bf16 v[20:23], v[178:181], v[216:219], v[20:23]
	v_mfma_f32_16x16x32_bf16 v[16:19], v[186:189], v[216:219], v[16:19]
	v_mfma_f32_16x16x32_bf16 v[4:7], v[178:181], v[224:227], v[4:7]
	v_mfma_f32_16x16x32_bf16 v[0:3], v[186:189], v[224:227], v[0:3]
	v_mfma_f32_16x16x32_bf16 v[52:55], v[182:185], v[204:207], v[52:55]
	v_mfma_f32_16x16x32_bf16 v[48:51], v[190:193], v[204:207], v[48:51]
	v_mfma_f32_16x16x32_bf16 v[36:39], v[182:185], v[212:215], v[36:39]
	v_mfma_f32_16x16x32_bf16 v[32:35], v[190:193], v[212:215], v[32:35]
	v_mfma_f32_16x16x32_bf16 v[20:23], v[182:185], v[220:223], v[20:23]
	v_mfma_f32_16x16x32_bf16 v[16:19], v[190:193], v[220:223], v[16:19]
	v_mfma_f32_16x16x32_bf16 v[4:7], v[182:185], v[228:231], v[4:7]
	v_mfma_f32_16x16x32_bf16 v[0:3], v[190:193], v[228:231], v[0:3]
	s_setprio 0
	s_barrier
	s_add_i32 s72, s72, 2
	s_add_u32 s51, s51, 0x100
	s_addc_u32 s53, s53, 0
	s_add_u32 s58, s58, 0x100
	s_addc_u32 s59, s59, 0
	s_cmp_gt_u32 s72, 13
	s_cbranch_scc0 .LBB0_152
	s_and_b64 vcc, exec, s[48:49]
	s_cbranch_vccz .LBB0_155
	s_barrier

;     __device__ __forceinline__ void prefetch(Pre& p, const Unit& u, int wr, int fr, int fq) const { prefetch_ss(p, ss, u, wr, fr, fq); }
;     __device__ __forceinline__ void prefetch(Pre& p, const Unit& u, int wr, int fr, int fq) const { prefetch_ss(p, ss, u, wr, fr, fq); }
;     __device__ __forceinline__ void prefetch(Pre& p, const Unit& u, int wr, int fr, int fq) const { prefetch_ss(p, ss, u, wr, fr, fq); }
; #define PG8_STAGE(bufoff, gbase, voff) do { _Pragma("unroll") for (int _i = 0; _i < 2; ++_i) \
;         __builtin_amdgcn_global_load_lds((const unsigned*)((const char*)(gbase) + (voff)[_i]), (PG8_LAS unsigned*)(lds + (bufoff) + ldsw + _i * 8192), 16, 0, 0); } while (0)
; #define PG8_LDA(dst, b, h) do { _Pragma("unroll") for (int m = 0; m < 4; ++m) _Pragma("unroll") for (int k = 0; k < 2; ++k) dst[m][k] = *(const PG8_LAS bf16x8*)(lds + PG8_SA(b, h) + aoff + m * 2048 + k * 1024); } while (0)
; #define PG8_BAR __builtin_amdgcn_s_barrier()
; template <class Epi, class Sched, bool ALIGN_EPI = false, bool SP2 = false>
; __device__ __forceinline__ void gemm_phase(PG8_LAS unsigned char* lds, const Gemm g, const Sched& S, const Epi& E) {
;     ...
;         const bool has_next = S.next(ui + 1, nxt);
;         typename Epi::Pre pre; E.prefetch(pre, cur, wr, fr, fq);
;         const char* nA = has_next ? (const char*)g.A + (size_t)nxt.pm * tstep : cA; const char* nB = has_next ? (const char*)g.Bt + (size_t)nxt.pn * tstep : cB;
;         for (int t = 0; t < nt; t += 2) {
;             const bool last = (t == nt - 2);
;             const char* a1 = cA + (size_t)(t + 1) * kstep;
;             const char* a2 = last ? nA : cA + (size_t)(t + 2) * kstep; const char* b2 = last ? nB : cB + (size_t)(t + 2) * kstep;
;             const char* a3 = a2 + kstep; const char* b3 = b2 + kstep;
;             if (last && has_next) S.a_ready(nxt);
;             if constexpr (SP2) {
;             PG8_LDB(B0, 0, 0); PG8_LDB(B1, 0, 1); PG8_SCHED; PG8_LDA(At, 0, 0); PG8_STAGE(PG8_SA(1, 1), a1 + hstep, voffA);
;             PG8_WAIT_V(8); PG8_WAIT_L(0); PG8_BAR; PG8_MMA(0, 0, At, B0); PG8_MMA(0, 1, At, B1); PG8_BAR; PG8_SCHED;
;             PG8_LDA(At, 0, 1); PG8_STAGE(PG8_SB(0, 0), b2, voffB); PG8_STAGE(PG8_SB(0, 1), b2 + hstep, voffB); PG8_STAGE(PG8_SA(0, 0), a2, voffA);
;             PG8_WAIT_V(8); PG8_WAIT_L(0); PG8_BAR; PG8_MMA(1, 0, At, B0); PG8_MMA(1, 1, At, B1); PG8_BAR; PG8_SCHED;
.LBB0_173:
	s_ashr_i32 s55, s54, 31
	s_lshl_b64 s[20:21], s[54:55], 19
	v_readlane_b32 s26, v255, 23
	v_readlane_b32 s27, v255, 24
	s_add_u32 s56, s26, s20
	s_addc_u32 s57, s27, s21
	s_and_b64 s[20:21], s[42:43], exec
	s_cselect_b32 s26, s57, s63
	s_cselect_b32 s27, s56, s62
	s_ashr_i32 s53, s52, 31
	s_lshl_b64 s[20:21], s[52:53], 19
	s_add_u32 s58, s2, s20
	s_addc_u32 s59, s35, s21
	s_and_b64 s[20:21], s[42:43], exec
	s_cselect_b32 s39, s59, s61
	s_cselect_b32 s53, s58, s60
	s_add_u32 s55, s60, 0x100
	s_addc_u32 s73, s61, 0
	s_add_u32 s60, s62, 0x40080
	s_addc_u32 s61, s63, 0
	s_mov_b32 s74, -2
	s_cmp_eq_u32 s72, 1
	s_cbranch_scc1 .Lzero_g2
.Lpeel_g2:
	s_add_u32 s5, s60, 0xfffc0080
	s_addc_u32 s8, s61, -1
	s_add_i32 s10, 0, 0x10000
	s_cmp_eq_u32 s74, 12
	s_cselect_b32 s65, s26, s8
	s_cselect_b32 s64, s27, s5
	s_cselect_b32 s63, s39, s73
	s_cselect_b32 s62, s53, s55
	s_add_i32 s5, 0, 0x14000
	v_add_u32_e32 v124, s10, v240
	v_add_u32_e32 v156, s5, v240
	ds_read_b128 v[112:115], v124
	ds_read_b128 v[116:119], v124 offset:1024
	ds_read_b128 v[120:123], v124 offset:2048
	ds_read_b128 v[124:127], v124 offset:3072
	ds_read_b128 v[136:139], v156
	ds_read_b128 v[140:143], v156 offset:1024
	ds_read_b128 v[152:155], v156 offset:2048
	ds_read_b128 v[156:159], v156 offset:3072
	v_lshl_add_u64 v[214:215], s[60:61], 0, v[208:209]
	s_add_i32 m0, s67, 0xc000
	ds_read_b128 v[164:167], v242
	ds_read_b128 v[172:175], v242 offset:1024
	ds_read_b128 v[176:179], v242 offset:2048
	ds_read_b128 v[180:183], v242 offset:3072
	ds_read_b128 v[184:187], v242 offset:4096
	ds_read_b128 v[188:191], v242 offset:5120
	ds_read_b128 v[192:195], v242 offset:6144
	ds_read_b128 v[210:213], v242 offset:7168
	global_load_lds_dwordx4 v[214:215], off
	v_lshl_add_u64 v[214:215], s[60:61], 0, v[206:207]
	s_add_i32 m0, s67, 0xe000
	s_nop 0
	global_load_lds_dwordx4 v[214:215], off
	s_waitcnt vmcnt(32)
	s_waitcnt lgkmcnt(0)
	s_barrier
	s_setprio 1
	s_waitcnt lgkmcnt(0)
	v_mfma_f32_16x16x32_bf16 v[168:171], v[112:115], v[164:167], 0
	v_mfma_f32_16x16x32_bf16 v[160:163], v[120:123], v[164:167], 0
	v_mfma_f32_16x16x32_bf16 v[108:111], v[112:115], v[176:179], 0
	v_mfma_f32_16x16x32_bf16 v[104:107], v[120:123], v[176:179], 0
	v_mfma_f32_16x16x32_bf16 v[92:95], v[112:115], v[184:187], 0
	v_mfma_f32_16x16x32_bf16 v[88:91], v[120:123], v[184:187], 0
	v_mfma_f32_16x16x32_bf16 v[76:79], v[112:115], v[192:195], 0
	v_mfma_f32_16x16x32_bf16 v[72:75], v[120:123], v[192:195], 0
	v_mfma_f32_16x16x32_bf16 v[168:171], v[116:119], v[172:175], v[168:171]
	v_mfma_f32_16x16x32_bf16 v[160:163], v[124:127], v[172:175], v[160:163]
	v_mfma_f32_16x16x32_bf16 v[108:111], v[116:119], v[180:183], v[108:111]
	v_mfma_f32_16x16x32_bf16 v[104:107], v[124:127], v[180:183], v[104:107]
	v_mfma_f32_16x16x32_bf16 v[92:95], v[116:119], v[188:191], v[92:95]
	v_mfma_f32_16x16x32_bf16 v[88:91], v[124:127], v[188:191], v[88:91]
	v_mfma_f32_16x16x32_bf16 v[76:79], v[116:119], v[210:213], v[76:79]
	v_mfma_f32_16x16x32_bf16 v[72:75], v[124:127], v[210:213], v[72:75]
	s_setprio 0
	s_setprio 1
	v_mfma_f32_16x16x32_bf16 v[132:135], v[136:139], v[164:167], 0
	v_mfma_f32_16x16x32_bf16 v[128:131], v[152:155], v[164:167], 0
	v_mfma_f32_16x16x32_bf16 v[100:103], v[136:139], v[176:179], 0
	v_mfma_f32_16x16x32_bf16 v[96:99], v[152:155], v[176:179], 0
	v_mfma_f32_16x16x32_bf16 v[84:87], v[136:139], v[184:187], 0
	v_mfma_f32_16x16x32_bf16 v[80:83], v[152:155], v[184:187], 0
	v_mfma_f32_16x16x32_bf16 v[68:71], v[136:139], v[192:195], 0
	v_mfma_f32_16x16x32_bf16 v[64:67], v[152:155], v[192:195], 0
	v_mfma_f32_16x16x32_bf16 v[132:135], v[140:143], v[172:175], v[132:135]
	v_mfma_f32_16x16x32_bf16 v[128:131], v[156:159], v[172:175], v[128:131]
	v_mfma_f32_16x16x32_bf16 v[100:103], v[140:143], v[180:183], v[100:103]
	v_mfma_f32_16x16x32_bf16 v[96:99], v[156:159], v[180:183], v[96:99]
	v_mfma_f32_16x16x32_bf16 v[84:87], v[140:143], v[188:191], v[84:87]
	v_mfma_f32_16x16x32_bf16 v[80:83], v[156:159], v[188:191], v[80:83]
	v_mfma_f32_16x16x32_bf16 v[68:71], v[140:143], v[210:213], v[68:71]
	v_mfma_f32_16x16x32_bf16 v[64:67], v[156:159], v[210:213], v[64:67]
	s_setprio 0
	s_barrier
	s_add_i32 s8, s10, s66
	v_lshl_add_u64 v[214:215], s[62:63], 0, v[202:203]
	s_mov_b32 m0, s8
	ds_read_b128 v[164:167], v242 offset:16384
	ds_read_b128 v[172:175], v242 offset:17408
	ds_read_b128 v[176:179], v242 offset:18432
	ds_read_b128 v[180:183], v242 offset:19456
	ds_read_b128 v[184:187], v242 offset:20480
	ds_read_b128 v[188:191], v242 offset:21504
	ds_read_b128 v[192:195], v242 offset:22528
	ds_read_b128 v[210:213], v242 offset:23552
	global_load_lds_dwordx4 v[214:215], off
	s_add_i32 m0, s8, 0x2000
	s_add_u32 s20, s62, 0x40000
	v_lshl_add_u64 v[216:217], s[62:63], 0, v[146:147]
	s_addc_u32 s21, s63, 0
	s_add_i32 s5, s5, s66
	global_load_lds_dwordx4 v[216:217], off
	v_lshl_add_u64 v[218:219], s[20:21], 0, v[202:203]
	s_mov_b32 m0, s5
	v_lshl_add_u64 v[220:221], s[64:65], 0, v[200:201]
	global_load_lds_dwordx4 v[218:219], off
	v_lshl_add_u64 v[218:219], s[20:21], 0, v[146:147]
	s_add_i32 m0, s5, 0x2000
	s_nop 0
	global_load_lds_dwordx4 v[218:219], off
	v_lshl_add_u64 v[218:219], s[64:65], 0, v[204:205]
	s_mov_b32 m0, s67
	s_nop 0
	global_load_lds_dwordx4 v[218:219], off
	s_mov_b32 m0, s68
	s_nop 0
	global_load_lds_dwordx4 v[220:221], off
	s_waitcnt vmcnt(32)
	s_waitcnt lgkmcnt(0)
	s_barrier
; #define PG8_MMA(ai, bj, At, Bt) do { __builtin_amdgcn_s_setprio(1); _Pragma("unroll") for (int m = 0; m < 4; ++m) _Pragma("unroll") for (int n = 0; n < 2; ++n) _Pragma("unroll") for (int k = 0; k < 2; ++k) \
;         acc[ai][bj][m][n] = __builtin_amdgcn_mfma_f32_16x16x32_bf16(Bt[n][k], At[m][k], acc[ai][bj][m][n], 0, 0, 0); __builtin_amdgcn_s_setprio(0); } while (0)
; #define PG8_WAIT_V(n) asm volatile("s_waitcnt vmcnt(" #n ")" ::: "memory")
; #define PG8_WAIT_L(n) asm volatile("s_waitcnt lgkmcnt(" #n ")" ::: "memory")
; #define PG8_BAR __builtin_amdgcn_s_barrier()
; #define PG8_SCHED __builtin_amdgcn_sched_barrier(0)
; template <class Epi, class Sched, bool ALIGN_EPI = false, bool SP2 = false>
; __device__ __forceinline__ void gemm_phase(PG8_LAS unsigned char* lds, const Gemm g, const Sched& S, const Epi& E) {
;     ...
;             PG8_WAIT_V(8); PG8_WAIT_L(0); PG8_BAR; PG8_MMA(1, 0, At, B0); PG8_MMA(1, 1, At, B1); PG8_BAR; PG8_SCHED;
;     ...
; #pragma unroll
;         for (int a = 0; a < 2; ++a)
; #pragma unroll
;             for (int b = 0; b < 2; ++b)
; #pragma unroll
;                 for (int m = 0; m < 4; ++m)
; #pragma unroll
;                     for (int n = 0; n < 2; ++n) acc[a][b][m][n] = (f32x4){0.f, 0.f, 0.f, 0.f};
	s_setprio 1
	s_waitcnt lgkmcnt(0)
	v_mfma_f32_16x16x32_bf16 v[60:63], v[112:115], v[164:167], 0
	v_mfma_f32_16x16x32_bf16 v[56:59], v[120:123], v[164:167], 0
	v_mfma_f32_16x16x32_bf16 v[44:47], v[112:115], v[176:179], 0
	v_mfma_f32_16x16x32_bf16 v[40:43], v[120:123], v[176:179], 0
	v_mfma_f32_16x16x32_bf16 v[28:31], v[112:115], v[184:187], 0
	v_mfma_f32_16x16x32_bf16 v[24:27], v[120:123], v[184:187], 0
	v_mfma_f32_16x16x32_bf16 v[12:15], v[112:115], v[192:195], 0
	v_mfma_f32_16x16x32_bf16 v[8:11], v[120:123], v[192:195], 0
	v_mfma_f32_16x16x32_bf16 v[60:63], v[116:119], v[172:175], v[60:63]
	v_mfma_f32_16x16x32_bf16 v[56:59], v[124:127], v[172:175], v[56:59]
	v_mfma_f32_16x16x32_bf16 v[44:47], v[116:119], v[180:183], v[44:47]
	v_mfma_f32_16x16x32_bf16 v[40:43], v[124:127], v[180:183], v[40:43]
	v_mfma_f32_16x16x32_bf16 v[28:31], v[116:119], v[188:191], v[28:31]
	v_mfma_f32_16x16x32_bf16 v[24:27], v[124:127], v[188:191], v[24:27]
	v_mfma_f32_16x16x32_bf16 v[12:15], v[116:119], v[210:213], v[12:15]
	v_mfma_f32_16x16x32_bf16 v[8:11], v[124:127], v[210:213], v[8:11]
	s_setprio 0
	s_setprio 1
	v_mfma_f32_16x16x32_bf16 v[52:55], v[136:139], v[164:167], 0
	v_mfma_f32_16x16x32_bf16 v[48:51], v[152:155], v[164:167], 0
	v_mfma_f32_16x16x32_bf16 v[36:39], v[136:139], v[176:179], 0
	v_mfma_f32_16x16x32_bf16 v[32:35], v[152:155], v[176:179], 0
	v_mfma_f32_16x16x32_bf16 v[20:23], v[136:139], v[184:187], 0
	v_mfma_f32_16x16x32_bf16 v[16:19], v[152:155], v[184:187], 0
	v_mfma_f32_16x16x32_bf16 v[4:7], v[136:139], v[192:195], 0
	v_mfma_f32_16x16x32_bf16 v[0:3], v[152:155], v[192:195], 0
	v_mfma_f32_16x16x32_bf16 v[52:55], v[140:143], v[172:175], v[52:55]
	v_mfma_f32_16x16x32_bf16 v[48:51], v[156:159], v[172:175], v[48:51]
	v_mfma_f32_16x16x32_bf16 v[36:39], v[140:143], v[180:183], v[36:39]
	v_mfma_f32_16x16x32_bf16 v[32:35], v[156:159], v[180:183], v[32:35]
	v_mfma_f32_16x16x32_bf16 v[20:23], v[140:143], v[188:191], v[20:23]
	v_mfma_f32_16x16x32_bf16 v[16:19], v[156:159], v[188:191], v[16:19]
	v_mfma_f32_16x16x32_bf16 v[4:7], v[140:143], v[210:213], v[4:7]
	v_mfma_f32_16x16x32_bf16 v[0:3], v[156:159], v[210:213], v[0:3]
	s_setprio 0
	s_barrier
	s_branch .Lmid_g2
.Lzero_g2:
	v_mov_b32_e32 v0, 0
	v_mov_b32_e32 v1, v0
	v_mov_b32_e32 v2, v0
	v_mov_b32_e32 v3, v0
	v_mov_b32_e32 v4, v0
	v_mov_b32_e32 v5, v0
	v_mov_b32_e32 v6, v0
	v_mov_b32_e32 v7, v0
	v_mov_b32_e32 v16, v0
	v_mov_b32_e32 v17, v0
	v_mov_b32_e32 v18, v0
	v_mov_b32_e32 v19, v0
	v_mov_b32_e32 v20, v0
	v_mov_b32_e32 v21, v0
	v_mov_b32_e32 v22, v0
	v_mov_b32_e32 v23, v0
	v_mov_b32_e32 v32, v0
	v_mov_b32_e32 v33, v0
	v_mov_b32_e32 v34, v0
	v_mov_b32_e32 v35, v0
	v_mov_b32_e32 v36, v0
	v_mov_b32_e32 v37, v0
	v_mov_b32_e32 v38, v0
	v_mov_b32_e32 v39, v0
	v_mov_b32_e32 v48, v0
	v_mov_b32_e32 v49, v0
	v_mov_b32_e32 v50, v0
	v_mov_b32_e32 v51, v0
	v_mov_b32_e32 v52, v0
	v_mov_b32_e32 v53, v0
	v_mov_b32_e32 v54, v0
	v_mov_b32_e32 v55, v0
	v_mov_b32_e32 v8, v0
	v_mov_b32_e32 v9, v0
	v_mov_b32_e32 v10, v0
	v_mov_b32_e32 v11, v0
	v_mov_b32_e32 v12, v0
	v_mov_b32_e32 v13, v0
	v_mov_b32_e32 v14, v0
	v_mov_b32_e32 v15, v0
	v_mov_b32_e32 v24, v0
	v_mov_b32_e32 v25, v0
	v_mov_b32_e32 v26, v0
	v_mov_b32_e32 v27, v0
	v_mov_b32_e32 v28, v0
	v_mov_b32_e32 v29, v0
	v_mov_b32_e32 v30, v0
	v_mov_b32_e32 v31, v0
	v_mov_b32_e32 v40, v0
	v_mov_b32_e32 v41, v0
	v_mov_b32_e32 v42, v0
	v_mov_b32_e32 v43, v0
	v_mov_b32_e32 v44, v0
	v_mov_b32_e32 v45, v0
	v_mov_b32_e32 v46, v0
	v_mov_b32_e32 v47, v0
	v_mov_b32_e32 v56, v0
	v_mov_b32_e32 v57, v0
	v_mov_b32_e32 v58, v0
	v_mov_b32_e32 v59, v0
	v_mov_b32_e32 v60, v0
	v_mov_b32_e32 v61, v0
	v_mov_b32_e32 v62, v0
	v_mov_b32_e32 v63, v0
	v_mov_b32_e32 v64, v0
	v_mov_b32_e32 v65, v0
	v_mov_b32_e32 v66, v0
	v_mov_b32_e32 v67, v0
	v_mov_b32_e32 v68, v0
	v_mov_b32_e32 v69, v0
	v_mov_b32_e32 v70, v0
	v_mov_b32_e32 v71, v0
	v_mov_b32_e32 v80, v0
	v_mov_b32_e32 v81, v0
	v_mov_b32_e32 v82, v0
	v_mov_b32_e32 v83, v0
	v_mov_b32_e32 v84, v0
	v_mov_b32_e32 v85, v0
	v_mov_b32_e32 v86, v0
	v_mov_b32_e32 v87, v0
	v_mov_b32_e32 v96, v0
	v_mov_b32_e32 v97, v0
	v_mov_b32_e32 v98, v0
	v_mov_b32_e32 v99, v0
	v_mov_b32_e32 v100, v0
	v_mov_b32_e32 v101, v0
	v_mov_b32_e32 v102, v0
	v_mov_b32_e32 v103, v0
	v_mov_b32_e32 v128, v0
	v_mov_b32_e32 v129, v0
	v_mov_b32_e32 v130, v0
	v_mov_b32_e32 v131, v0
	v_mov_b32_e32 v132, v0
	v_mov_b32_e32 v133, v0
	v_mov_b32_e32 v134, v0
	v_mov_b32_e32 v135, v0
	v_mov_b32_e32 v72, v0
	v_mov_b32_e32 v73, v0
	v_mov_b32_e32 v74, v0
	v_mov_b32_e32 v75, v0
	v_mov_b32_e32 v76, v0
	v_mov_b32_e32 v77, v0
	v_mov_b32_e32 v78, v0
	v_mov_b32_e32 v79, v0
	v_mov_b32_e32 v88, v0
	v_mov_b32_e32 v89, v0
	v_mov_b32_e32 v90, v0
	v_mov_b32_e32 v91, v0
	v_mov_b32_e32 v92, v0
	v_mov_b32_e32 v93, v0
	v_mov_b32_e32 v94, v0
	v_mov_b32_e32 v95, v0
	v_mov_b32_e32 v104, v0
	v_mov_b32_e32 v105, v0
	v_mov_b32_e32 v106, v0
	v_mov_b32_e32 v107, v0
	v_mov_b32_e32 v108, v0
	v_mov_b32_e32 v109, v0
	v_mov_b32_e32 v110, v0
	v_mov_b32_e32 v111, v0
	v_mov_b32_e32 v160, v0
	v_mov_b32_e32 v161, v0
	v_mov_b32_e32 v162, v0
	v_mov_b32_e32 v163, v0
	v_mov_b32_e32 v168, v0
	v_mov_b32_e32 v169, v0
	v_mov_b32_e32 v170, v0
	v_mov_b32_e32 v171, v0

; #define PG8_STAGE(bufoff, gbase, voff) do { _Pragma("unroll") for (int _i = 0; _i < 2; ++_i) \
;         __builtin_amdgcn_global_load_lds((const unsigned*)((const char*)(gbase) + (voff)[_i]), (PG8_LAS unsigned*)(lds + (bufoff) + ldsw + _i * 8192), 16, 0, 0); } while (0)
; #define PG8_LDA(dst, b, h) do { _Pragma("unroll") for (int m = 0; m < 4; ++m) _Pragma("unroll") for (int k = 0; k < 2; ++k) dst[m][k] = *(const PG8_LAS bf16x8*)(lds + PG8_SA(b, h) + aoff + m * 2048 + k * 1024); } while (0)
; #define PG8_LDB(dst, b, h) do { _Pragma("unroll") for (int n = 0; n < 2; ++n) _Pragma("unroll") for (int k = 0; k < 2; ++k) dst[n][k] = *(const PG8_LAS bf16x8*)(lds + PG8_SB(b, h) + boff + n * 2048 + k * 1024); } while (0)
; #define PG8_MMA(ai, bj, At, Bt) do { __builtin_amdgcn_s_setprio(1); _Pragma("unroll") for (int m = 0; m < 4; ++m) _Pragma("unroll") for (int n = 0; n < 2; ++n) _Pragma("unroll") for (int k = 0; k < 2; ++k) \
;         acc[ai][bj][m][n] = __builtin_amdgcn_mfma_f32_16x16x32_bf16(Bt[n][k], At[m][k], acc[ai][bj][m][n], 0, 0, 0); __builtin_amdgcn_s_setprio(0); } while (0)
; #define PG8_WAIT_V(n) asm volatile("s_waitcnt vmcnt(" #n ")" ::: "memory")
; #define PG8_WAIT_L(n) asm volatile("s_waitcnt lgkmcnt(" #n ")" ::: "memory")
; #define PG8_BAR __builtin_amdgcn_s_barrier()
; #define PG8_SCHED __builtin_amdgcn_sched_barrier(0)
; template <class Epi, class Sched, bool ALIGN_EPI = false, bool SP2 = false>
; __device__ __forceinline__ void gemm_phase(PG8_LAS unsigned char* lds, const Gemm g, const Sched& S, const Epi& E) {
;     ...
;             PG8_LDB(B0, 1, 0); PG8_LDB(B1, 1, 1); PG8_SCHED; PG8_LDA(At, 1, 0); PG8_STAGE(PG8_SA(0, 1), a2 + hstep, voffA);
;             PG8_WAIT_V(8); PG8_WAIT_L(0); PG8_BAR; PG8_MMA(0, 0, At, B0); PG8_MMA(0, 1, At, B1); PG8_BAR; PG8_SCHED;
.Lmid_g2:
	s_add_i32 s5, 0, 0x18000
	s_add_i32 s8, 0, 0x1c000
	v_add_u32_e32 v124, s5, v240
	v_add_u32_e32 v156, s8, v240
	ds_read_b128 v[112:115], v124
	ds_read_b128 v[116:119], v124 offset:1024
	ds_read_b128 v[120:123], v124 offset:2048
	ds_read_b128 v[124:127], v124 offset:3072
	ds_read_b128 v[136:139], v156
	ds_read_b128 v[140:143], v156 offset:1024
	ds_read_b128 v[152:155], v156 offset:2048
	ds_read_b128 v[156:159], v156 offset:3072
	s_add_u32 s20, s64, 0x40000
	s_addc_u32 s21, s65, 0
	s_mov_b32 m0, s69
	v_lshl_add_u64 v[222:223], s[20:21], 0, v[204:205]
	ds_read_b128 v[164:167], v242 offset:32768
	ds_read_b128 v[172:175], v242 offset:33792
	ds_read_b128 v[176:179], v242 offset:34816
	ds_read_b128 v[180:183], v242 offset:35840
	ds_read_b128 v[184:187], v242 offset:36864
	ds_read_b128 v[188:191], v242 offset:37888
	ds_read_b128 v[192:195], v242 offset:38912
	ds_read_b128 v[210:213], v242 offset:39936
	global_load_lds_dwordx4 v[222:223], off
	v_lshl_add_u64 v[222:223], s[20:21], 0, v[200:201]
	s_mov_b32 m0, s70
	s_nop 0
	global_load_lds_dwordx4 v[222:223], off
	s_waitcnt vmcnt(8)
	s_waitcnt lgkmcnt(0)
	s_barrier
	s_setprio 1
	s_waitcnt lgkmcnt(0)
	v_mfma_f32_16x16x32_bf16 v[168:171], v[112:115], v[164:167], v[168:171]
	v_mfma_f32_16x16x32_bf16 v[160:163], v[120:123], v[164:167], v[160:163]
	v_mfma_f32_16x16x32_bf16 v[108:111], v[112:115], v[176:179], v[108:111]
	v_mfma_f32_16x16x32_bf16 v[104:107], v[120:123], v[176:179], v[104:107]
	v_mfma_f32_16x16x32_bf16 v[92:95], v[112:115], v[184:187], v[92:95]
	v_mfma_f32_16x16x32_bf16 v[88:91], v[120:123], v[184:187], v[88:91]
	v_mfma_f32_16x16x32_bf16 v[76:79], v[112:115], v[192:195], v[76:79]
	v_mfma_f32_16x16x32_bf16 v[72:75], v[120:123], v[192:195], v[72:75]
	v_mfma_f32_16x16x32_bf16 v[168:171], v[116:119], v[172:175], v[168:171]
	v_mfma_f32_16x16x32_bf16 v[160:163], v[124:127], v[172:175], v[160:163]
	v_mfma_f32_16x16x32_bf16 v[108:111], v[116:119], v[180:183], v[108:111]
	v_mfma_f32_16x16x32_bf16 v[104:107], v[124:127], v[180:183], v[104:107]
	v_mfma_f32_16x16x32_bf16 v[92:95], v[116:119], v[188:191], v[92:95]
	v_mfma_f32_16x16x32_bf16 v[88:91], v[124:127], v[188:191], v[88:91]
	v_mfma_f32_16x16x32_bf16 v[76:79], v[116:119], v[210:213], v[76:79]
	v_mfma_f32_16x16x32_bf16 v[72:75], v[124:127], v[210:213], v[72:75]
	s_setprio 0
	s_setprio 1
	v_mfma_f32_16x16x32_bf16 v[132:135], v[136:139], v[164:167], v[132:135]
	v_mfma_f32_16x16x32_bf16 v[128:131], v[152:155], v[164:167], v[128:131]
	v_mfma_f32_16x16x32_bf16 v[100:103], v[136:139], v[176:179], v[100:103]
	v_mfma_f32_16x16x32_bf16 v[96:99], v[152:155], v[176:179], v[96:99]
	v_mfma_f32_16x16x32_bf16 v[84:87], v[136:139], v[184:187], v[84:87]
	v_mfma_f32_16x16x32_bf16 v[80:83], v[152:155], v[184:187], v[80:83]
	v_mfma_f32_16x16x32_bf16 v[68:71], v[136:139], v[192:195], v[68:71]
	v_mfma_f32_16x16x32_bf16 v[64:67], v[152:155], v[192:195], v[64:67]
	v_mfma_f32_16x16x32_bf16 v[132:135], v[140:143], v[172:175], v[132:135]
	v_mfma_f32_16x16x32_bf16 v[128:131], v[156:159], v[172:175], v[128:131]
	v_mfma_f32_16x16x32_bf16 v[100:103], v[140:143], v[180:183], v[100:103]
	v_mfma_f32_16x16x32_bf16 v[96:99], v[156:159], v[180:183], v[96:99]
	v_mfma_f32_16x16x32_bf16 v[84:87], v[140:143], v[188:191], v[84:87]
	v_mfma_f32_16x16x32_bf16 v[80:83], v[156:159], v[188:191], v[80:83]
	v_mfma_f32_16x16x32_bf16 v[68:71], v[140:143], v[210:213], v[68:71]
	v_mfma_f32_16x16x32_bf16 v[64:67], v[156:159], v[210:213], v[64:67]
	s_setprio 0
	s_barrier
; #define PG8_STAGE(bufoff, gbase, voff) do { _Pragma("unroll") for (int _i = 0; _i < 2; ++_i) \
;         __builtin_amdgcn_global_load_lds((const unsigned*)((const char*)(gbase) + (voff)[_i]), (PG8_LAS unsigned*)(lds + (bufoff) + ldsw + _i * 8192), 16, 0, 0); } while (0)
; #define PG8_LDA(dst, b, h) do { _Pragma("unroll") for (int m = 0; m < 4; ++m) _Pragma("unroll") for (int k = 0; k < 2; ++k) dst[m][k] = *(const PG8_LAS bf16x8*)(lds + PG8_SA(b, h) + aoff + m * 2048 + k * 1024); } while (0)
; #define PG8_MMA(ai, bj, At, Bt) do { __builtin_amdgcn_s_setprio(1); _Pragma("unroll") for (int m = 0; m < 4; ++m) _Pragma("unroll") for (int n = 0; n < 2; ++n) _Pragma("unroll") for (int k = 0; k < 2; ++k) \
;         acc[ai][bj][m][n] = __builtin_amdgcn_mfma_f32_16x16x32_bf16(Bt[n][k], At[m][k], acc[ai][bj][m][n], 0, 0, 0); __builtin_amdgcn_s_setprio(0); } while (0)
; #define PG8_WAIT_V(n) asm volatile("s_waitcnt vmcnt(" #n ")" ::: "memory")
; #define PG8_WAIT_L(n) asm volatile("s_waitcnt lgkmcnt(" #n ")" ::: "memory")
; #define PG8_BAR __builtin_amdgcn_s_barrier()
; #define PG8_SCHED __builtin_amdgcn_sched_barrier(0)
; template <class Epi, class Sched, bool ALIGN_EPI = false, bool SP2 = false>
; __device__ __forceinline__ void gemm_phase(PG8_LAS unsigned char* lds, const Gemm g, const Sched& S, const Epi& E) {
;     ...
;         for (int t = 0; t < nt; t += 2) {
;     ...
;             PG8_LDA(At, 1, 1); PG8_STAGE(PG8_SB(1, 0), b3, voffB); PG8_STAGE(PG8_SB(1, 1), b3 + hstep, voffB); PG8_STAGE(PG8_SA(1, 0), a3, voffA);
;             PG8_WAIT_V(8); PG8_WAIT_L(0); PG8_BAR; PG8_MMA(1, 0, At, B0); PG8_MMA(1, 1, At, B1); PG8_BAR; PG8_SCHED;
;     ...
;         if constexpr (ALIGN_EPI) { if (wr == 0) PG8_BAR; }
	s_add_i32 s5, s5, s66
	v_lshl_add_u64 v[214:215], v[214:215], 0, s[22:23]
	s_mov_b32 m0, s5
	ds_read_b128 v[164:167], v242 offset:49152
	ds_read_b128 v[172:175], v242 offset:50176
	ds_read_b128 v[176:179], v242 offset:51200
	ds_read_b128 v[180:183], v242 offset:52224
	ds_read_b128 v[184:187], v242 offset:53248
	ds_read_b128 v[188:191], v242 offset:54272
	ds_read_b128 v[192:195], v242 offset:55296
	ds_read_b128 v[210:213], v242 offset:56320
	global_load_lds_dwordx4 v[214:215], off
	s_add_i32 m0, s5, 0x2000
	s_add_u32 s20, s62, 0x40080
	v_lshl_add_u64 v[214:215], v[216:217], 0, s[22:23]
	s_addc_u32 s21, s63, 0
	s_add_i32 s5, s8, s66
	global_load_lds_dwordx4 v[214:215], off
	v_lshl_add_u64 v[214:215], s[20:21], 0, v[202:203]
	s_mov_b32 m0, s5
	s_nop 0
	global_load_lds_dwordx4 v[214:215], off
	v_lshl_add_u64 v[214:215], s[20:21], 0, v[146:147]
	s_add_i32 m0, s5, 0x2000
	s_nop 0
	global_load_lds_dwordx4 v[214:215], off
	v_lshl_add_u64 v[214:215], v[218:219], 0, s[22:23]
	s_mov_b32 m0, s34
	s_nop 0
	global_load_lds_dwordx4 v[214:215], off
	v_lshl_add_u64 v[214:215], v[220:221], 0, s[22:23]
	s_mov_b32 m0, s71
	s_nop 0
	global_load_lds_dwordx4 v[214:215], off
	s_waitcnt vmcnt(8)
	s_waitcnt lgkmcnt(0)
	s_barrier
	s_setprio 1
	s_waitcnt lgkmcnt(0)
	v_mfma_f32_16x16x32_bf16 v[60:63], v[112:115], v[164:167], v[60:63]
	v_mfma_f32_16x16x32_bf16 v[56:59], v[120:123], v[164:167], v[56:59]
	v_mfma_f32_16x16x32_bf16 v[44:47], v[112:115], v[176:179], v[44:47]
	v_mfma_f32_16x16x32_bf16 v[40:43], v[120:123], v[176:179], v[40:43]
	v_mfma_f32_16x16x32_bf16 v[28:31], v[112:115], v[184:187], v[28:31]
	v_mfma_f32_16x16x32_bf16 v[24:27], v[120:123], v[184:187], v[24:27]
	v_mfma_f32_16x16x32_bf16 v[12:15], v[112:115], v[192:195], v[12:15]
	v_mfma_f32_16x16x32_bf16 v[8:11], v[120:123], v[192:195], v[8:11]
	v_mfma_f32_16x16x32_bf16 v[60:63], v[116:119], v[172:175], v[60:63]
	v_mfma_f32_16x16x32_bf16 v[56:59], v[124:127], v[172:175], v[56:59]
	v_mfma_f32_16x16x32_bf16 v[44:47], v[116:119], v[180:183], v[44:47]
	v_mfma_f32_16x16x32_bf16 v[40:43], v[124:127], v[180:183], v[40:43]
	v_mfma_f32_16x16x32_bf16 v[28:31], v[116:119], v[188:191], v[28:31]
	v_mfma_f32_16x16x32_bf16 v[24:27], v[124:127], v[188:191], v[24:27]
	v_mfma_f32_16x16x32_bf16 v[12:15], v[116:119], v[210:213], v[12:15]
	v_mfma_f32_16x16x32_bf16 v[8:11], v[124:127], v[210:213], v[8:11]
	s_setprio 0
	s_setprio 1
	v_mfma_f32_16x16x32_bf16 v[52:55], v[136:139], v[164:167], v[52:55]
	v_mfma_f32_16x16x32_bf16 v[48:51], v[152:155], v[164:167], v[48:51]
	v_mfma_f32_16x16x32_bf16 v[36:39], v[136:139], v[176:179], v[36:39]
	v_mfma_f32_16x16x32_bf16 v[32:35], v[152:155], v[176:179], v[32:35]
	v_mfma_f32_16x16x32_bf16 v[20:23], v[136:139], v[184:187], v[20:23]
	v_mfma_f32_16x16x32_bf16 v[16:19], v[152:155], v[184:187], v[16:19]
	v_mfma_f32_16x16x32_bf16 v[4:7], v[136:139], v[192:195], v[4:7]
	v_mfma_f32_16x16x32_bf16 v[0:3], v[152:155], v[192:195], v[0:3]
	v_mfma_f32_16x16x32_bf16 v[52:55], v[140:143], v[172:175], v[52:55]
	v_mfma_f32_16x16x32_bf16 v[48:51], v[156:159], v[172:175], v[48:51]
	v_mfma_f32_16x16x32_bf16 v[36:39], v[140:143], v[180:183], v[36:39]
	v_mfma_f32_16x16x32_bf16 v[32:35], v[156:159], v[180:183], v[32:35]
	v_mfma_f32_16x16x32_bf16 v[20:23], v[140:143], v[188:191], v[20:23]
	v_mfma_f32_16x16x32_bf16 v[16:19], v[156:159], v[188:191], v[16:19]
	v_mfma_f32_16x16x32_bf16 v[4:7], v[140:143], v[210:213], v[4:7]
	v_mfma_f32_16x16x32_bf16 v[0:3], v[156:159], v[210:213], v[0:3]
	s_setprio 0
	s_barrier
	s_add_i32 s74, s74, 2
	s_add_u32 s55, s55, 0x100
	s_addc_u32 s73, s73, 0
	s_add_u32 s60, s60, 0x100
	s_addc_u32 s61, s61, 0
	s_cmp_gt_u32 s74, 13
	s_cbranch_scc0 .LBB0_174
	s_and_b64 vcc, exec, s[50:51]
	s_cbranch_vccz .LBB0_177
	s_barrier

;     __device__ __forceinline__ void prefetch(Pre& p, const Unit& u, int wr, int fr, int fq) const { prefetch_ss(p, ss, u, wr, fr, fq); }
;     __device__ __forceinline__ void prefetch(Pre& p, const Unit& u, int wr, int fr, int fq) const { prefetch_ss(p, ss, u, wr, fr, fq); }
;     __device__ __forceinline__ void prefetch(Pre& p, const Unit& u, int wr, int fr, int fq) const { prefetch_ss(p, ss, u, wr, fr, fq); }
; template <class Epi, class Sched, bool ALIGN_EPI = false, bool SP2 = false>
; __device__ __forceinline__ void gemm_phase(PG8_LAS unsigned char* lds, const Gemm g, const Sched& S, const Epi& E) {
;     ...
;         const bool has_next = S.next(ui + 1, nxt);
;         typename Epi::Pre pre; E.prefetch(pre, cur, wr, fr, fq);
;         const char* nA = has_next ? (const char*)g.A + (size_t)nxt.pm * tstep : cA; const char* nB = has_next ? (const char*)g.Bt + (size_t)nxt.pn * tstep : cB;
;         for (int t = 0; t < nt; t += 2) {
;             const bool last = (t == nt - 2);
;             const char* a1 = cA + (size_t)(t + 1) * kstep;
;             const char* a2 = last ? nA : cA + (size_t)(t + 2) * kstep; const char* b2 = last ? nB : cB + (size_t)(t + 2) * kstep;
;             const char* a3 = a2 + kstep; const char* b3 = b2 + kstep;
;             if (last && has_next) S.a_ready(nxt);
.LBB0_413:
	v_lshl_add_u32 v152, s2, 8, v155
	v_ashrrev_i32_e32 v153, 31, v152
	v_lshl_add_u64 v[0:1], v[152:153], 3, v[136:137]
	global_load_dwordx2 v[146:147], v[0:1], off
	global_load_dwordx2 v[142:143], v[0:1], off offset:128
	s_ashr_i32 s49, s48, 31
	s_lshl_b64 s[26:27], s[48:49], 19
	s_add_u32 s50, s28, s26
	s_addc_u32 s51, s29, s27
	s_and_b64 s[26:27], s[42:43], exec
	s_cselect_b32 s4, s51, s55
	s_cselect_b32 s26, s50, s54
	s_ashr_i32 s47, s46, 31
	s_lshl_b64 s[52:53], s[46:47], 19
	s_add_u32 s52, s34, s52
	s_addc_u32 s53, s35, s53
	s_and_b64 s[56:57], s[42:43], exec
	s_cselect_b32 s27, s53, s45
	s_cselect_b32 s36, s52, s44
	s_add_u32 s47, s44, 0x100
	s_addc_u32 s49, s45, 0
	s_add_u32 s44, s54, 0x40080
	s_addc_u32 s45, s55, 0
	s_mov_b32 s69, -2
	s_cmp_eq_u32 s66, 1
	s_cbranch_scc1 .Lzero_g1e
; #define PG8_STAGE(bufoff, gbase, voff) do { _Pragma("unroll") for (int _i = 0; _i < 2; ++_i) \
;         __builtin_amdgcn_global_load_lds((const unsigned*)((const char*)(gbase) + (voff)[_i]), (PG8_LAS unsigned*)(lds + (bufoff) + ldsw + _i * 8192), 16, 0, 0); } while (0)
; #define PG8_LDA(dst, b, h) do { _Pragma("unroll") for (int m = 0; m < 4; ++m) _Pragma("unroll") for (int k = 0; k < 2; ++k) dst[m][k] = *(const PG8_LAS bf16x8*)(lds + PG8_SA(b, h) + aoff + m * 2048 + k * 1024); } while (0)
; #define PG8_LDB(dst, b, h) do { _Pragma("unroll") for (int n = 0; n < 2; ++n) _Pragma("unroll") for (int k = 0; k < 2; ++k) dst[n][k] = *(const PG8_LAS bf16x8*)(lds + PG8_SB(b, h) + boff + n * 2048 + k * 1024); } while (0)
; #define PG8_MMA(ai, bj, At, Bt) do { __builtin_amdgcn_s_setprio(1); _Pragma("unroll") for (int m = 0; m < 4; ++m) _Pragma("unroll") for (int n = 0; n < 2; ++n) _Pragma("unroll") for (int k = 0; k < 2; ++k) \
;         acc[ai][bj][m][n] = __builtin_amdgcn_mfma_f32_16x16x32_bf16(Bt[n][k], At[m][k], acc[ai][bj][m][n], 0, 0, 0); __builtin_amdgcn_s_setprio(0); } while (0)
; #define PG8_WAIT_V(n) asm volatile("s_waitcnt vmcnt(" #n ")" ::: "memory")
; #define PG8_WAIT_L(n) asm volatile("s_waitcnt lgkmcnt(" #n ")" ::: "memory")
; #define PG8_BAR __builtin_amdgcn_s_barrier()
; #define PG8_SCHED __builtin_amdgcn_sched_barrier(0)
; template <class Epi, class Sched, bool ALIGN_EPI = false, bool SP2 = false>
; __device__ __forceinline__ void gemm_phase(PG8_LAS unsigned char* lds, const Gemm g, const Sched& S, const Epi& E) {
;     ...
;             PG8_LDB(B0, 0, 0); PG8_LDB(B1, 0, 1); PG8_SCHED; PG8_LDA(At, 0, 0); PG8_STAGE(PG8_SA(1, 1), a1 + hstep, voffA);
;             PG8_WAIT_V(8); PG8_WAIT_L(0); PG8_BAR; PG8_MMA(0, 0, At, B0); PG8_MMA(0, 1, At, B1); PG8_BAR; PG8_SCHED;
;             PG8_LDA(At, 0, 1); PG8_STAGE(PG8_SB(0, 0), b2, voffB); PG8_STAGE(PG8_SB(0, 1), b2 + hstep, voffB); PG8_STAGE(PG8_SA(0, 0), a2, voffA);
;             PG8_WAIT_V(8); PG8_WAIT_L(0); PG8_BAR; PG8_MMA(1, 0, At, B0); PG8_MMA(1, 1, At, B1); PG8_BAR; PG8_SCHED;
.Lpeel_g1e:
	s_add_u32 s8, s44, 0xfffc0080
	s_addc_u32 s10, s45, -1
	s_add_i32 s12, 0, 0x10000
	s_cmp_eq_u32 s69, 12
	s_cselect_b32 s57, s4, s10
	s_cselect_b32 s56, s26, s8
	v_add_u32_e32 v154, s12, v157
	s_cselect_b32 s55, s27, s49
	s_cselect_b32 s54, s36, s47
	s_add_i32 s8, 0, 0x14000
	ds_read_b128 v[162:165], v154
	ds_read_b128 v[166:169], v154 offset:1024
	ds_read_b128 v[170:173], v154 offset:2048
	ds_read_b128 v[174:177], v154 offset:3072
	v_add_u32_e32 v154, s8, v157
	ds_read_b128 v[178:181], v154
	ds_read_b128 v[182:185], v154 offset:1024
	ds_read_b128 v[186:189], v154 offset:2048
	ds_read_b128 v[190:193], v154 offset:3072
	v_lshl_add_u64 v[194:195], s[44:45], 0, v[140:141]
	s_add_i32 m0, s58, 0xc000
	ds_read_b128 v[200:203], v161
	ds_read_b128 v[204:207], v161 offset:1024
	ds_read_b128 v[208:211], v161 offset:2048
	ds_read_b128 v[212:215], v161 offset:3072
	ds_read_b128 v[216:219], v161 offset:4096
	ds_read_b128 v[220:223], v161 offset:5120
	ds_read_b128 v[224:227], v161 offset:6144
	ds_read_b128 v[228:231], v161 offset:7168
	global_load_lds_dwordx4 v[194:195], off
	v_lshl_add_u64 v[194:195], s[44:45], 0, v[138:139]
	s_add_i32 m0, s58, 0xe000
	s_nop 0
	global_load_lds_dwordx4 v[194:195], off
	s_waitcnt vmcnt(26)
	s_waitcnt lgkmcnt(0)
	s_barrier
	s_setprio 1
	s_waitcnt lgkmcnt(0)
	v_mfma_f32_16x16x32_bf16 v[124:127], v[162:165], v[200:203], 0
	v_mfma_f32_16x16x32_bf16 v[120:123], v[170:173], v[200:203], 0
	v_mfma_f32_16x16x32_bf16 v[108:111], v[162:165], v[208:211], 0
	v_mfma_f32_16x16x32_bf16 v[104:107], v[170:173], v[208:211], 0
	v_mfma_f32_16x16x32_bf16 v[92:95], v[162:165], v[216:219], 0
	v_mfma_f32_16x16x32_bf16 v[88:91], v[170:173], v[216:219], 0
	v_mfma_f32_16x16x32_bf16 v[76:79], v[162:165], v[224:227], 0
	v_mfma_f32_16x16x32_bf16 v[72:75], v[170:173], v[224:227], 0
	v_mfma_f32_16x16x32_bf16 v[124:127], v[166:169], v[204:207], v[124:127]
	v_mfma_f32_16x16x32_bf16 v[120:123], v[174:177], v[204:207], v[120:123]
	v_mfma_f32_16x16x32_bf16 v[108:111], v[166:169], v[212:215], v[108:111]
	v_mfma_f32_16x16x32_bf16 v[104:107], v[174:177], v[212:215], v[104:107]
	v_mfma_f32_16x16x32_bf16 v[92:95], v[166:169], v[220:223], v[92:95]
	v_mfma_f32_16x16x32_bf16 v[88:91], v[174:177], v[220:223], v[88:91]
	v_mfma_f32_16x16x32_bf16 v[76:79], v[166:169], v[228:231], v[76:79]
	v_mfma_f32_16x16x32_bf16 v[72:75], v[174:177], v[228:231], v[72:75]
	s_setprio 0
	s_setprio 1
	v_mfma_f32_16x16x32_bf16 v[116:119], v[178:181], v[200:203], 0
	v_mfma_f32_16x16x32_bf16 v[112:115], v[186:189], v[200:203], 0
	v_mfma_f32_16x16x32_bf16 v[100:103], v[178:181], v[208:211], 0
	v_mfma_f32_16x16x32_bf16 v[96:99], v[186:189], v[208:211], 0
	v_mfma_f32_16x16x32_bf16 v[84:87], v[178:181], v[216:219], 0
	v_mfma_f32_16x16x32_bf16 v[80:83], v[186:189], v[216:219], 0
	v_mfma_f32_16x16x32_bf16 v[68:71], v[178:181], v[224:227], 0
	v_mfma_f32_16x16x32_bf16 v[64:67], v[186:189], v[224:227], 0
	v_mfma_f32_16x16x32_bf16 v[116:119], v[182:185], v[204:207], v[116:119]
	v_mfma_f32_16x16x32_bf16 v[112:115], v[190:193], v[204:207], v[112:115]
	v_mfma_f32_16x16x32_bf16 v[100:103], v[182:185], v[212:215], v[100:103]
	v_mfma_f32_16x16x32_bf16 v[96:99], v[190:193], v[212:215], v[96:99]
	v_mfma_f32_16x16x32_bf16 v[84:87], v[182:185], v[220:223], v[84:87]
	v_mfma_f32_16x16x32_bf16 v[80:83], v[190:193], v[220:223], v[80:83]
	v_mfma_f32_16x16x32_bf16 v[68:71], v[182:185], v[228:231], v[68:71]
	v_mfma_f32_16x16x32_bf16 v[64:67], v[190:193], v[228:231], v[64:67]
	s_setprio 0
	s_barrier
	s_add_i32 s10, s12, s39
	v_lshl_add_u64 v[194:195], s[54:55], 0, v[132:133]
	s_mov_b32 m0, s10
	ds_read_b128 v[200:203], v161 offset:16384
	ds_read_b128 v[204:207], v161 offset:17408
	ds_read_b128 v[208:211], v161 offset:18432
	ds_read_b128 v[212:215], v161 offset:19456
	ds_read_b128 v[216:219], v161 offset:20480
	ds_read_b128 v[220:223], v161 offset:21504
	ds_read_b128 v[224:227], v161 offset:22528
	ds_read_b128 v[228:231], v161 offset:23552
	global_load_lds_dwordx4 v[194:195], off
	s_add_i32 m0, s10, 0x2000
	s_add_u32 s70, s54, 0x40000
	v_lshl_add_u64 v[240:241], s[54:55], 0, v[128:129]
	s_addc_u32 s71, s55, 0
	s_add_i32 s8, s8, s39
	global_load_lds_dwordx4 v[240:241], off
	v_lshl_add_u64 v[242:243], s[70:71], 0, v[132:133]
	s_mov_b32 m0, s8
	v_lshl_add_u64 v[244:245], s[56:57], 0, v[130:131]
	global_load_lds_dwordx4 v[242:243], off
	v_lshl_add_u64 v[242:243], s[70:71], 0, v[128:129]
	s_add_i32 m0, s8, 0x2000
	s_nop 0
	global_load_lds_dwordx4 v[242:243], off
	v_lshl_add_u64 v[242:243], s[56:57], 0, v[134:135]
	s_mov_b32 m0, s58
	s_nop 0
	global_load_lds_dwordx4 v[242:243], off
	s_mov_b32 m0, s59
	s_nop 0
	global_load_lds_dwordx4 v[244:245], off
	s_waitcnt vmcnt(26)
	s_waitcnt lgkmcnt(0)
	s_barrier
	s_setprio 1
	s_waitcnt lgkmcnt(0)
	v_mfma_f32_16x16x32_bf16 v[60:63], v[162:165], v[200:203], 0
	v_mfma_f32_16x16x32_bf16 v[56:59], v[170:173], v[200:203], 0
	v_mfma_f32_16x16x32_bf16 v[44:47], v[162:165], v[208:211], 0
	v_mfma_f32_16x16x32_bf16 v[40:43], v[170:173], v[208:211], 0
	v_mfma_f32_16x16x32_bf16 v[28:31], v[162:165], v[216:219], 0
	v_mfma_f32_16x16x32_bf16 v[24:27], v[170:173], v[216:219], 0
	v_mfma_f32_16x16x32_bf16 v[12:15], v[162:165], v[224:227], 0
	v_mfma_f32_16x16x32_bf16 v[8:11], v[170:173], v[224:227], 0
	v_mfma_f32_16x16x32_bf16 v[60:63], v[166:169], v[204:207], v[60:63]
	v_mfma_f32_16x16x32_bf16 v[56:59], v[174:177], v[204:207], v[56:59]
	v_mfma_f32_16x16x32_bf16 v[44:47], v[166:169], v[212:215], v[44:47]
	v_mfma_f32_16x16x32_bf16 v[40:43], v[174:177], v[212:215], v[40:43]
	v_mfma_f32_16x16x32_bf16 v[28:31], v[166:169], v[220:223], v[28:31]
	v_mfma_f32_16x16x32_bf16 v[24:27], v[174:177], v[220:223], v[24:27]
	v_mfma_f32_16x16x32_bf16 v[12:15], v[166:169], v[228:231], v[12:15]
	v_mfma_f32_16x16x32_bf16 v[8:11], v[174:177], v[228:231], v[8:11]
	s_setprio 0
	s_setprio 1
	v_mfma_f32_16x16x32_bf16 v[52:55], v[178:181], v[200:203], 0
	v_mfma_f32_16x16x32_bf16 v[48:51], v[186:189], v[200:203], 0
	v_mfma_f32_16x16x32_bf16 v[36:39], v[178:181], v[208:211], 0
	v_mfma_f32_16x16x32_bf16 v[32:35], v[186:189], v[208:211], 0
	v_mfma_f32_16x16x32_bf16 v[20:23], v[178:181], v[216:219], 0
	v_mfma_f32_16x16x32_bf16 v[16:19], v[186:189], v[216:219], 0
	v_mfma_f32_16x16x32_bf16 v[4:7], v[178:181], v[224:227], 0
	v_mfma_f32_16x16x32_bf16 v[0:3], v[186:189], v[224:227], 0
	v_mfma_f32_16x16x32_bf16 v[52:55], v[182:185], v[204:207], v[52:55]
	v_mfma_f32_16x16x32_bf16 v[48:51], v[190:193], v[204:207], v[48:51]
	v_mfma_f32_16x16x32_bf16 v[36:39], v[182:185], v[212:215], v[36:39]
	v_mfma_f32_16x16x32_bf16 v[32:35], v[190:193], v[212:215], v[32:35]
	v_mfma_f32_16x16x32_bf16 v[20:23], v[182:185], v[220:223], v[20:23]
	v_mfma_f32_16x16x32_bf16 v[16:19], v[190:193], v[220:223], v[16:19]
	v_mfma_f32_16x16x32_bf16 v[4:7], v[182:185], v[228:231], v[4:7]
	v_mfma_f32_16x16x32_bf16 v[0:3], v[190:193], v[228:231], v[0:3]
	s_setprio 0
	s_barrier
	s_branch .Lmid_g1e

; #define PG8_STAGE(bufoff, gbase, voff) do { _Pragma("unroll") for (int _i = 0; _i < 2; ++_i) \
;         __builtin_amdgcn_global_load_lds((const unsigned*)((const char*)(gbase) + (voff)[_i]), (PG8_LAS unsigned*)(lds + (bufoff) + ldsw + _i * 8192), 16, 0, 0); } while (0)
; #define PG8_LDA(dst, b, h) do { _Pragma("unroll") for (int m = 0; m < 4; ++m) _Pragma("unroll") for (int k = 0; k < 2; ++k) dst[m][k] = *(const PG8_LAS bf16x8*)(lds + PG8_SA(b, h) + aoff + m * 2048 + k * 1024); } while (0)
; #define PG8_LDB(dst, b, h) do { _Pragma("unroll") for (int n = 0; n < 2; ++n) _Pragma("unroll") for (int k = 0; k < 2; ++k) dst[n][k] = *(const PG8_LAS bf16x8*)(lds + PG8_SB(b, h) + boff + n * 2048 + k * 1024); } while (0)
; #define PG8_MMA(ai, bj, At, Bt) do { __builtin_amdgcn_s_setprio(1); _Pragma("unroll") for (int m = 0; m < 4; ++m) _Pragma("unroll") for (int n = 0; n < 2; ++n) _Pragma("unroll") for (int k = 0; k < 2; ++k) \
;         acc[ai][bj][m][n] = __builtin_amdgcn_mfma_f32_16x16x32_bf16(Bt[n][k], At[m][k], acc[ai][bj][m][n], 0, 0, 0); __builtin_amdgcn_s_setprio(0); } while (0)
; #define PG8_WAIT_V(n) asm volatile("s_waitcnt vmcnt(" #n ")" ::: "memory")
; #define PG8_WAIT_L(n) asm volatile("s_waitcnt lgkmcnt(" #n ")" ::: "memory")
; #define PG8_BAR __builtin_amdgcn_s_barrier()
; #define PG8_SCHED __builtin_amdgcn_sched_barrier(0)
; template <class Epi, class Sched, bool ALIGN_EPI = false, bool SP2 = false>
; __device__ __forceinline__ void gemm_phase(PG8_LAS unsigned char* lds, const Gemm g, const Sched& S, const Epi& E) {
;     ...
;             PG8_LDB(B0, 1, 0); PG8_LDB(B1, 1, 1); PG8_SCHED; PG8_LDA(At, 1, 0); PG8_STAGE(PG8_SA(0, 1), a2 + hstep, voffA);
;             PG8_WAIT_V(8); PG8_WAIT_L(0); PG8_BAR; PG8_MMA(0, 0, At, B0); PG8_MMA(0, 1, At, B1); PG8_BAR; PG8_SCHED;
.Lmid_g1e:
	s_add_i32 s8, 0, 0x18000
	v_add_u32_e32 v154, s8, v157
	s_add_i32 s10, 0, 0x1c000
	ds_read_b128 v[162:165], v154
	ds_read_b128 v[166:169], v154 offset:1024
	ds_read_b128 v[170:173], v154 offset:2048
	ds_read_b128 v[174:177], v154 offset:3072
	v_add_u32_e32 v154, s10, v157
	ds_read_b128 v[178:181], v154
	ds_read_b128 v[182:185], v154 offset:1024
	ds_read_b128 v[186:189], v154 offset:2048
	ds_read_b128 v[190:193], v154 offset:3072
	s_add_u32 s56, s56, 0x40000
	s_addc_u32 s57, s57, 0
	s_mov_b32 m0, s60
	v_lshl_add_u64 v[246:247], s[56:57], 0, v[134:135]
	ds_read_b128 v[200:203], v161 offset:32768
	ds_read_b128 v[204:207], v161 offset:33792
	ds_read_b128 v[208:211], v161 offset:34816
	ds_read_b128 v[212:215], v161 offset:35840
	ds_read_b128 v[216:219], v161 offset:36864
	ds_read_b128 v[220:223], v161 offset:37888
	ds_read_b128 v[224:227], v161 offset:38912
	ds_read_b128 v[228:231], v161 offset:39936
	global_load_lds_dwordx4 v[246:247], off
	v_lshl_add_u64 v[246:247], s[56:57], 0, v[130:131]
	s_mov_b32 m0, s61
	s_nop 0
	global_load_lds_dwordx4 v[246:247], off
	s_waitcnt vmcnt(8)
	s_waitcnt lgkmcnt(0)
	s_barrier
	s_setprio 1
	s_waitcnt lgkmcnt(0)
	v_mfma_f32_16x16x32_bf16 v[124:127], v[162:165], v[200:203], v[124:127]
	v_mfma_f32_16x16x32_bf16 v[120:123], v[170:173], v[200:203], v[120:123]
	v_mfma_f32_16x16x32_bf16 v[108:111], v[162:165], v[208:211], v[108:111]
	v_mfma_f32_16x16x32_bf16 v[104:107], v[170:173], v[208:211], v[104:107]
	v_mfma_f32_16x16x32_bf16 v[92:95], v[162:165], v[216:219], v[92:95]
	v_mfma_f32_16x16x32_bf16 v[88:91], v[170:173], v[216:219], v[88:91]
	v_mfma_f32_16x16x32_bf16 v[76:79], v[162:165], v[224:227], v[76:79]
	v_mfma_f32_16x16x32_bf16 v[72:75], v[170:173], v[224:227], v[72:75]
	v_mfma_f32_16x16x32_bf16 v[124:127], v[166:169], v[204:207], v[124:127]
	v_mfma_f32_16x16x32_bf16 v[120:123], v[174:177], v[204:207], v[120:123]
	v_mfma_f32_16x16x32_bf16 v[108:111], v[166:169], v[212:215], v[108:111]
	v_mfma_f32_16x16x32_bf16 v[104:107], v[174:177], v[212:215], v[104:107]
	v_mfma_f32_16x16x32_bf16 v[92:95], v[166:169], v[220:223], v[92:95]
	v_mfma_f32_16x16x32_bf16 v[88:91], v[174:177], v[220:223], v[88:91]
	v_mfma_f32_16x16x32_bf16 v[76:79], v[166:169], v[228:231], v[76:79]
	v_mfma_f32_16x16x32_bf16 v[72:75], v[174:177], v[228:231], v[72:75]
	s_setprio 0
	s_setprio 1
	v_mfma_f32_16x16x32_bf16 v[116:119], v[178:181], v[200:203], v[116:119]
	v_mfma_f32_16x16x32_bf16 v[112:115], v[186:189], v[200:203], v[112:115]
	v_mfma_f32_16x16x32_bf16 v[100:103], v[178:181], v[208:211], v[100:103]
	v_mfma_f32_16x16x32_bf16 v[96:99], v[186:189], v[208:211], v[96:99]
	v_mfma_f32_16x16x32_bf16 v[84:87], v[178:181], v[216:219], v[84:87]
	v_mfma_f32_16x16x32_bf16 v[80:83], v[186:189], v[216:219], v[80:83]
	v_mfma_f32_16x16x32_bf16 v[68:71], v[178:181], v[224:227], v[68:71]
	v_mfma_f32_16x16x32_bf16 v[64:67], v[186:189], v[224:227], v[64:67]
	v_mfma_f32_16x16x32_bf16 v[116:119], v[182:185], v[204:207], v[116:119]
	v_mfma_f32_16x16x32_bf16 v[112:115], v[190:193], v[204:207], v[112:115]
	v_mfma_f32_16x16x32_bf16 v[100:103], v[182:185], v[212:215], v[100:103]
	v_mfma_f32_16x16x32_bf16 v[96:99], v[190:193], v[212:215], v[96:99]
	v_mfma_f32_16x16x32_bf16 v[84:87], v[182:185], v[220:223], v[84:87]
	v_mfma_f32_16x16x32_bf16 v[80:83], v[190:193], v[220:223], v[80:83]
	v_mfma_f32_16x16x32_bf16 v[68:71], v[182:185], v[228:231], v[68:71]
	v_mfma_f32_16x16x32_bf16 v[64:67], v[190:193], v[228:231], v[64:67]
	s_setprio 0
	s_barrier
; #define PG8_STAGE(bufoff, gbase, voff) do { _Pragma("unroll") for (int _i = 0; _i < 2; ++_i) \
;         __builtin_amdgcn_global_load_lds((const unsigned*)((const char*)(gbase) + (voff)[_i]), (PG8_LAS unsigned*)(lds + (bufoff) + ldsw + _i * 8192), 16, 0, 0); } while (0)
; #define PG8_LDA(dst, b, h) do { _Pragma("unroll") for (int m = 0; m < 4; ++m) _Pragma("unroll") for (int k = 0; k < 2; ++k) dst[m][k] = *(const PG8_LAS bf16x8*)(lds + PG8_SA(b, h) + aoff + m * 2048 + k * 1024); } while (0)
; #define PG8_MMA(ai, bj, At, Bt) do { __builtin_amdgcn_s_setprio(1); _Pragma("unroll") for (int m = 0; m < 4; ++m) _Pragma("unroll") for (int n = 0; n < 2; ++n) _Pragma("unroll") for (int k = 0; k < 2; ++k) \
;         acc[ai][bj][m][n] = __builtin_amdgcn_mfma_f32_16x16x32_bf16(Bt[n][k], At[m][k], acc[ai][bj][m][n], 0, 0, 0); __builtin_amdgcn_s_setprio(0); } while (0)
; #define PG8_WAIT_V(n) asm volatile("s_waitcnt vmcnt(" #n ")" ::: "memory")
; #define PG8_WAIT_L(n) asm volatile("s_waitcnt lgkmcnt(" #n ")" ::: "memory")
; #define PG8_BAR __builtin_amdgcn_s_barrier()
; #define PG8_SCHED __builtin_amdgcn_sched_barrier(0)
; template <class Epi, class Sched, bool ALIGN_EPI = false, bool SP2 = false>
; __device__ __forceinline__ void gemm_phase(PG8_LAS unsigned char* lds, const Gemm g, const Sched& S, const Epi& E) {
;     ...
;         for (int t = 0; t < nt; t += 2) {
;     ...
;             PG8_LDA(At, 1, 1); PG8_STAGE(PG8_SB(1, 0), b3, voffB); PG8_STAGE(PG8_SB(1, 1), b3 + hstep, voffB); PG8_STAGE(PG8_SA(1, 0), a3, voffA);
;             PG8_WAIT_V(8); PG8_WAIT_L(0); PG8_BAR; PG8_MMA(1, 0, At, B0); PG8_MMA(1, 1, At, B1); PG8_BAR; PG8_SCHED;
;     ...
;         if constexpr (ALIGN_EPI) { if (wr == 0) PG8_BAR; }
	s_add_i32 s8, s8, s39
	v_lshl_add_u64 v[194:195], v[194:195], 0, s[22:23]
	s_mov_b32 m0, s8
	ds_read_b128 v[200:203], v161 offset:49152
	ds_read_b128 v[204:207], v161 offset:50176
	ds_read_b128 v[208:211], v161 offset:51200
	ds_read_b128 v[212:215], v161 offset:52224
	ds_read_b128 v[216:219], v161 offset:53248
	ds_read_b128 v[220:223], v161 offset:54272
	ds_read_b128 v[224:227], v161 offset:55296
	ds_read_b128 v[228:231], v161 offset:56320
	global_load_lds_dwordx4 v[194:195], off
	s_add_i32 m0, s8, 0x2000
	s_add_u32 s54, s54, 0x40080
	v_lshl_add_u64 v[194:195], v[240:241], 0, s[22:23]
	s_addc_u32 s55, s55, 0
	s_add_i32 s8, s10, s39
	global_load_lds_dwordx4 v[194:195], off
	v_lshl_add_u64 v[194:195], s[54:55], 0, v[132:133]
	s_mov_b32 m0, s8
	s_nop 0
	global_load_lds_dwordx4 v[194:195], off
	v_lshl_add_u64 v[194:195], s[54:55], 0, v[128:129]
	s_add_i32 m0, s8, 0x2000
	s_nop 0
	global_load_lds_dwordx4 v[194:195], off
	v_lshl_add_u64 v[194:195], v[242:243], 0, s[22:23]
	s_mov_b32 m0, s64
	s_nop 0
	global_load_lds_dwordx4 v[194:195], off
	v_lshl_add_u64 v[194:195], v[244:245], 0, s[22:23]
	s_mov_b32 m0, s65
	s_nop 0
	global_load_lds_dwordx4 v[194:195], off
	s_waitcnt vmcnt(8)
	s_waitcnt lgkmcnt(0)
	s_barrier
	s_setprio 1
	s_waitcnt lgkmcnt(0)
	v_mfma_f32_16x16x32_bf16 v[60:63], v[162:165], v[200:203], v[60:63]
	v_mfma_f32_16x16x32_bf16 v[56:59], v[170:173], v[200:203], v[56:59]
	v_mfma_f32_16x16x32_bf16 v[44:47], v[162:165], v[208:211], v[44:47]
	v_mfma_f32_16x16x32_bf16 v[40:43], v[170:173], v[208:211], v[40:43]
	v_mfma_f32_16x16x32_bf16 v[28:31], v[162:165], v[216:219], v[28:31]
	v_mfma_f32_16x16x32_bf16 v[24:27], v[170:173], v[216:219], v[24:27]
	v_mfma_f32_16x16x32_bf16 v[12:15], v[162:165], v[224:227], v[12:15]
	v_mfma_f32_16x16x32_bf16 v[8:11], v[170:173], v[224:227], v[8:11]
	v_mfma_f32_16x16x32_bf16 v[60:63], v[166:169], v[204:207], v[60:63]
	v_mfma_f32_16x16x32_bf16 v[56:59], v[174:177], v[204:207], v[56:59]
	v_mfma_f32_16x16x32_bf16 v[44:47], v[166:169], v[212:215], v[44:47]
	v_mfma_f32_16x16x32_bf16 v[40:43], v[174:177], v[212:215], v[40:43]
	v_mfma_f32_16x16x32_bf16 v[28:31], v[166:169], v[220:223], v[28:31]
	v_mfma_f32_16x16x32_bf16 v[24:27], v[174:177], v[220:223], v[24:27]
	v_mfma_f32_16x16x32_bf16 v[12:15], v[166:169], v[228:231], v[12:15]
	v_mfma_f32_16x16x32_bf16 v[8:11], v[174:177], v[228:231], v[8:11]
	s_setprio 0
	s_setprio 1
	v_mfma_f32_16x16x32_bf16 v[52:55], v[178:181], v[200:203], v[52:55]
	v_mfma_f32_16x16x32_bf16 v[48:51], v[186:189], v[200:203], v[48:51]
	v_mfma_f32_16x16x32_bf16 v[36:39], v[178:181], v[208:211], v[36:39]
	v_mfma_f32_16x16x32_bf16 v[32:35], v[186:189], v[208:211], v[32:35]
	v_mfma_f32_16x16x32_bf16 v[20:23], v[178:181], v[216:219], v[20:23]
	v_mfma_f32_16x16x32_bf16 v[16:19], v[186:189], v[216:219], v[16:19]
	v_mfma_f32_16x16x32_bf16 v[4:7], v[178:181], v[224:227], v[4:7]
	v_mfma_f32_16x16x32_bf16 v[0:3], v[186:189], v[224:227], v[0:3]
	v_mfma_f32_16x16x32_bf16 v[52:55], v[182:185], v[204:207], v[52:55]
	v_mfma_f32_16x16x32_bf16 v[48:51], v[190:193], v[204:207], v[48:51]
	v_mfma_f32_16x16x32_bf16 v[36:39], v[182:185], v[212:215], v[36:39]
	v_mfma_f32_16x16x32_bf16 v[32:35], v[190:193], v[212:215], v[32:35]
	v_mfma_f32_16x16x32_bf16 v[20:23], v[182:185], v[220:223], v[20:23]
	v_mfma_f32_16x16x32_bf16 v[16:19], v[190:193], v[220:223], v[16:19]
	v_mfma_f32_16x16x32_bf16 v[4:7], v[182:185], v[228:231], v[4:7]
	v_mfma_f32_16x16x32_bf16 v[0:3], v[190:193], v[228:231], v[0:3]
	s_setprio 0
	s_barrier
	s_add_i32 s69, s69, 2
	s_add_u32 s47, s47, 0x100
	s_addc_u32 s49, s49, 0
	s_add_u32 s44, s44, 0x100
	s_addc_u32 s45, s45, 0
	s_cmp_gt_u32 s69, 13
	s_cbranch_scc0 .LBB0_414
	s_and_b64 vcc, exec, s[20:21]
	s_cbranch_vccz .LBB0_417
	s_barrier
